# P2a S4 per-lane address set-up hoisted from the unit loop into the P2a preheader (registers freed by re-pooling the S3 epilogue temporaries)
# speedup vs baseline: 1.0059x; 1.0035x over previous
; __device__ __forceinline__ void gdn_prep_phase(LAS unsigned char* lds, const GdnPrepArgs& A, int bid, int G, const unsigned char* zero_page) {
;     ...
;         const int which = w >> 2, rt = (w >> 1) & 1, ct = w & 1, r = lane & 31, hh = lane >> 5;
;         const LAS unsigned char* ia = lds + (which ? L_QN : L_KN) + (32 * rt + r) * QS_ + 16 * hh;
;         const LAS unsigned char* ib = lds + L_KN + (32 * ct + r) * QS_ + 16 * hh;
;         f32x16 acc = zero16();
; #pragma unroll
;         for (int ks = 0; ks < 8; ++ks) acc = MFMA32(*(const LAS bf16x8*)(ia + 32 * ks), *(const LAS bf16x8*)(ib + 32 * ks), acc);
;         const LAS float* sc = (const LAS float*)(lds + L_SC);
;         const int j = 32 * ct + r; const float gfj = sc[j], gbj = sc[64 + j];
; #pragma unroll
;         for (int reg = 0; reg < 16; ++reg) {
;             const int i = 32 * rt + (reg & 3) + 8 * (reg >> 2) + 4 * hh; const float val = acc[reg];
;             const float ef = __expf(sc[i] - gfj), eb = __expf(sc[64 + i] - gbj);
;             if (which == 0) {
;                 const float lf = (i > j) ? sc[128 + i] * val * ef : 0.f, lb = (i < j) ? sc[192 + i] * val * eb : 0.f;
;                 ((LAS float*)(lds + L_LPF))[i * 64 + (j & 3) * 16 + (j >> 2)] = lf;
;                 const int i2 = 63 - i, j2 = 63 - j;
;                 ((LAS float*)(lds + L_LPB))[i2 * 64 + (j2 & 3) * 16 + (j2 >> 2)] = lb;
;             } else {
;                 const float af = (i >= j) ? QSCALE * val * ef : 0.f, ab = (i <= j) ? QSCALE * val * eb : 0.f;
;                 *(LAS unsigned short*)(lds + L_AF + i * AS_ + j * 2) = (unsigned short)(pkbf(af, 0.f) & 0xffffu);
;                 *(LAS unsigned short*)(lds + L_AB + i * AS_ + j * 2) = (unsigned short)(pkbf(ab, 0.f) & 0xffffu);
;             }
;         }
;     }
;     LBAR();
;     if (!(pflg & 16)) {
;         const int dir = w >> 2, li = (w & 3) * 64 + lane, j = li >> 2, q = li & 3;
;         const LAS float* LP = (const LAS float*)(lds + (dir ? L_LPB : L_LPF)) + q * 16;
;         float t[16];
; #pragma unroll
;         for (int a = 0; a < 16; ++a) t[a] = 0.f;
;         f32x4 lq[3][4];
;     ...
;         SOLVE_LD(0); SOLVE_LD(1);
; #pragma unroll
;         for (int i = 0; i < 64; ++i) {
;             if (i + 2 < 48) SOLVE_LD(i + 2);
;             else if (i + 1 >= 48 && i + 1 < 64) SOLVE_LD(i + 1);
;             float p0 = 0.f, p1 = 0.f;
; #pragma unroll
.LBB0_197:
	s_and_b64 vcc, exec, s[2:3]
	s_cbranch_vccnz .LBB0_362
	s_lshl_b32 s67, s34, 4
	v_writelane_b32 v254, s42, 55
	s_lshl_b32 s3, s34, 3
	s_ashr_i32 s2, s67, 31
	v_writelane_b32 v254, s43, 56
	s_cmp_lt_i32 s34, 51
	v_writelane_b32 v254, s2, 57
	s_cselect_b64 s[4:5], -1, 0
	s_ashr_i32 s2, s38, 7
	s_bfe_u32 s6, s38, 0x10006
	v_writelane_b32 v254, s4, 59
	s_cmpk_gt_u32 s38, 0xff
	s_mov_b32 s7, 0x11000
	v_writelane_b32 v254, s5, 60
	s_cselect_b64 s[4:5], -1, 0
	s_cmpk_lt_u32 s38, 0x100
	s_mov_b32 s39, 0x15800
	s_cselect_b32 s7, s7, 0xcc00
	s_cselect_b32 s39, s39, 0x19800
	s_lshl_b32 s40, s2, 5
	v_and_b32_e32 v4, 31, v7
	s_add_i32 s7, s7, 0
	s_and_b32 s40, s40, 32
	v_or_b32_e32 v3, s40, v4
	v_mov_b32_e32 v6, s7
	s_movk_i32 s42, 0x110
	s_lshl_b32 s7, s6, 5
	v_lshrrev_b32_e32 v5, 5, v18
	v_mad_u32_u24 v11, v3, s42, v6
	v_or_b32_e32 v3, s7, v4
	v_lshlrev_b32_e32 v12, 4, v5
	v_lshl_or_b32 v15, v5, 2, s40
	v_lshlrev_b32_e32 v5, 1, v3
	s_add_i32 s40, 0, 0x1d800
	s_add_i32 s41, 0, 0x11000
	v_add_u32_e32 v8, s40, v5
	s_add_i32 s40, 0, 0x1fc00
	v_mov_b32_e32 v6, s41
	v_add_u32_e32 v9, s40, v5
	v_lshlrev_b32_e32 v5, 6, v7
	v_mad_u32_u24 v14, v3, s42, v6
	v_and_b32_e32 v5, 0xc0, v5
	s_add_i32 s40, 0, 0x15800
	v_bitop3_b32 v6, s7, 60, v4 bitop3:0xc8
	v_bitop3_b32 v4, s7, 63, v4 bitop3:0x36
	v_add3_u32 v13, s40, v5, v6
	v_lshlrev_b32_e32 v5, 4, v4
	v_lshrrev_b32_e32 v4, 2, v4
	v_and_b32_e32 v57, 15, v7
	v_and_or_b32 v16, v5, 48, v4
	v_lshl_or_b32 v4, s2, 4, v57
	s_movk_i32 s2, 0x90
	v_mul_lo_u32 v4, v4, s2
	s_lshl_b32 s2, s6, 6
	v_lshrrev_b32_e32 v6, 1, v7
	s_lshr_b32 s100, s38, 8
	s_and_b32 s38, s38, 0xc0
	s_mul_i32 s101, s100, 0xc0
	s_xor_b32 s101, s38, s101
	v_and_b32_e32 v58, 24, v6
	s_add_i32 s2, s2, 0
	v_add3_u32 v33, s2, v4, v58
	v_lshrrev_b32_e32 v4, 2, v7
	s_add_i32 s6, s38, 0
	v_lshlrev_b32_e32 v2, 1, v18
	v_or_b32_e32 v17, s101, v18
	s_lshr_b32 s101, s101, 6
	s_nop 0
	v_and_b32_e32 v59, 12, v4
	v_add_u32_e32 v62, s6, v58
	s_movk_i32 s6, 0x3fc
	v_readlane_b32 s42, v252, 62
	v_lshrrev_b32_e32 v32, 2, v17
	v_and_b32_e32 v249, 15, v32
	s_nop 0
	v_or_b32_e32 v4, s7, v59
	v_and_b32_e32 v60, 30, v2
	v_bitop3_b32 v2, v17, s6, v169 bitop3:0x6c
	v_mul_u32_u24_e32 v4, 0x110, v4
	v_add_u32_e32 v64, s42, v2
	v_lshlrev_b32_e32 v2, 1, v32
	v_add3_u32 v61, s41, v4, v60
	v_xor_b32_e32 v4, 0x7e, v2
	v_readlane_b32 s6, v252, 63
	s_or_b32 s52, s3, 7
	s_mulk_i32 s52, 0x300
	v_add_u32_e32 v34, s6, v4
	v_readlane_b32 s6, v254, 0
	s_or_b32 s53, s3, 1
	s_add_i32 s3, s52, 0xfffffd00
	v_add_u32_e32 v35, s6, v2
	v_cmp_gt_u32_e64 s[6:7], 2, v18
	v_and_b32_e32 v5, 3, v7
	s_add_i32 s39, s39, 0
	v_writelane_b32 v254, s6, 61
	v_and_b32_e32 v27, 64, v1
	v_lshl_add_u32 v56, v5, 6, s39
	v_writelane_b32 v254, s7, 62
	v_cmp_eq_u32_e64 s[6:7], 0, v18
	s_add_i32 s41, s41, s38
	v_bitop3_b32 v4, s38, v169, v18 bitop3:0xc8
	v_writelane_b32 v254, s6, 63
	v_xor_b32_e32 v21, 16, v1
	v_add_u32_e32 v27, 64, v27
	v_writelane_b32 v255, s7, 0
	v_writelane_b32 v255, s3, 1
	s_add_i32 s3, s52, 0xfffffa00
	v_writelane_b32 v255, s3, 3
	s_add_i32 s3, s52, 0xfffff700
	v_writelane_b32 v255, s3, 5
	s_add_i32 s3, s52, 0xfffff400
	v_writelane_b32 v255, s3, 7
	s_add_i32 s3, s52, 0xfffff100
	v_writelane_b32 v255, s3, 9
	s_add_i32 s3, s52, 0xffffee00
	v_writelane_b32 v255, s3, 11
	v_cmp_ge_u32_e64 s[38:39], v15, v3
	v_cmp_lt_i32_e32 vcc, v21, v27
	s_add_i32 s3, 0, 0x19800
	v_writelane_b32 v255, s38, 13
	v_cndmask_b32_e32 v21, v1, v21, vcc
	v_lshlrev_b32_e32 v69, 2, v21
	v_writelane_b32 v255, s39, 14
	v_cmp_gt_u32_e64 s[38:39], v15, v3
	v_xor_b32_e32 v21, 32, v1
	v_cmp_lt_i32_e32 vcc, v21, v27
	v_writelane_b32 v255, s38, 15
	v_lshlrev_b32_e32 v27, 6, v15
	v_add_u32_e32 v63, s41, v58
	v_writelane_b32 v255, s39, 16
	s_movk_i32 s38, 0xfc0
	v_bitop3_b32 v27, v16, s38, v27 bitop3:0x36
	v_lshl_add_u32 v73, v27, 2, s3
	v_or_b32_e32 v27, 1, v15
	v_lshl_add_u32 v74, v27, 2, s42
	v_cmp_lt_u32_e64 s[40:41], v27, v3
	v_lshlrev_b32_e32 v38, 8, v27
	v_lshlrev_b32_e32 v27, 6, v27
	v_cndmask_b32_e32 v21, v1, v21, vcc
	v_bitop3_b32 v27, v16, s38, v27 bitop3:0x36
	v_cmp_eq_u32_e32 vcc, 0, v249
	v_writelane_b32 v255, s40, 17
	v_lshl_add_u32 v75, v27, 2, s3
	v_or_b32_e32 v27, 2, v15
	v_cndmask_b32_e64 v104, 0, 1.0, vcc
	v_cmp_eq_u32_e32 vcc, 1, v249
	v_writelane_b32 v255, s41, 18
	v_cmp_lt_u32_e64 s[40:41], v27, v3
	v_cndmask_b32_e64 v105, 0, 1.0, vcc
	v_cmp_eq_u32_e32 vcc, 2, v249
	v_writelane_b32 v255, s40, 19
	v_lshl_add_u32 v76, v27, 2, s42
	v_cndmask_b32_e64 v106, 0, 1.0, vcc
	v_cmp_eq_u32_e32 vcc, 3, v249
	v_writelane_b32 v255, s41, 20
	v_cmp_gt_u32_e64 s[40:41], v27, v3
	v_lshlrev_b32_e32 v39, 8, v27
	v_lshlrev_b32_e32 v27, 6, v27
	v_cndmask_b32_e64 v107, 0, 1.0, vcc
	v_cmp_eq_u32_e32 vcc, 4, v249
	v_bitop3_b32 v27, v16, s38, v27 bitop3:0x36
	v_writelane_b32 v255, s40, 21
	v_cndmask_b32_e64 v109, 0, 1.0, vcc
	v_cmp_eq_u32_e32 vcc, 5, v249
	v_lshl_add_u32 v77, v27, 2, s3
	v_or_b32_e32 v27, 3, v15
	v_cndmask_b32_e64 v110, 0, 1.0, vcc
	v_cmp_eq_u32_e32 vcc, 6, v249
	v_writelane_b32 v255, s41, 22
	v_cmp_lt_u32_e64 s[40:41], v27, v3
	v_cndmask_b32_e64 v111, 0, 1.0, vcc
	v_cmp_eq_u32_e32 vcc, 7, v249
	v_writelane_b32 v255, s40, 23
	v_lshl_add_u32 v78, v27, 2, s42
	v_cndmask_b32_e64 v112, 0, 1.0, vcc
	v_cmp_eq_u32_e32 vcc, 8, v249
	v_writelane_b32 v255, s41, 24
	v_cmp_gt_u32_e64 s[40:41], v27, v3
	v_lshlrev_b32_e32 v40, 8, v27
	v_lshlrev_b32_e32 v27, 6, v27
	v_cndmask_b32_e64 v113, 0, 1.0, vcc
	v_cmp_eq_u32_e32 vcc, 9, v249
	v_bitop3_b32 v27, v16, s38, v27 bitop3:0x36
	v_writelane_b32 v255, s40, 25
	v_cndmask_b32_e64 v114, 0, 1.0, vcc
	v_cmp_eq_u32_e32 vcc, 10, v249
	v_lshl_add_u32 v79, v27, 2, s3
	v_or_b32_e32 v27, 8, v15
; #define LAS __attribute__((address_space(3)))
; __device__ __forceinline__ unsigned pkbf(float a, float b) { bf16x2_t v = __builtin_convertvector((f32x2_t){a, b}, bf16x2_t); return __builtin_bit_cast(unsigned, v); }
; __device__ __forceinline__ void gdn_prep_phase(LAS unsigned char* lds, const GdnPrepArgs& A, int bid, int G, const unsigned char* zero_page) {
;     ...
;             const int i = 32 * rt + (reg & 3) + 8 * (reg >> 2) + 4 * hh; const float val = acc[reg];
;             const float ef = __expf(sc[i] - gfj), eb = __expf(sc[64 + i] - gbj);
;             if (which == 0) {
;                 const float lf = (i > j) ? sc[128 + i] * val * ef : 0.f, lb = (i < j) ? sc[192 + i] * val * eb : 0.f;
;                 ((LAS float*)(lds + L_LPF))[i * 64 + (j & 3) * 16 + (j >> 2)] = lf;
;                 const int i2 = 63 - i, j2 = 63 - j;
;                 ((LAS float*)(lds + L_LPB))[i2 * 64 + (j2 & 3) * 16 + (j2 >> 2)] = lb;
;             } else {
;                 const float af = (i >= j) ? QSCALE * val * ef : 0.f, ab = (i <= j) ? QSCALE * val * eb : 0.f;
;                 *(LAS unsigned short*)(lds + L_AF + i * AS_ + j * 2) = (unsigned short)(pkbf(af, 0.f) & 0xffffu);
;                 *(LAS unsigned short*)(lds + L_AB + i * AS_ + j * 2) = (unsigned short)(pkbf(ab, 0.f) & 0xffffu);
;             }
;         }
;     }
;     LBAR();
;     if (!(pflg & 16)) {
;         const int dir = w >> 2, li = (w & 3) * 64 + lane, j = li >> 2, q = li & 3;
;         const LAS float* LP = (const LAS float*)(lds + (dir ? L_LPB : L_LPF)) + q * 16;
;         float t[16];
; #pragma unroll
;         for (int a = 0; a < 16; ++a) t[a] = 0.f;
;         f32x4 lq[3][4];
;     ...
;         SOLVE_LD(0); SOLVE_LD(1);
; #pragma unroll
;         for (int i = 0; i < 64; ++i) {
;             if (i + 2 < 48) SOLVE_LD(i + 2);
;             else if (i + 1 >= 48 && i + 1 < 64) SOLVE_LD(i + 1);
;             float p0 = 0.f, p1 = 0.f;
; #pragma unroll
;             for (int a4 = 0; a4 < (i + 15) / 16; ++a4) { const f32x4 lv = lq[i % 3][a4];
;                 p0 = __builtin_fmaf(lv.x, t[4 * a4], p0); p1 = __builtin_fmaf(lv.y, t[4 * a4 + 1], p1); p0 = __builtin_fmaf(lv.z, t[4 * a4 + 2], p0); p1 = __builtin_fmaf(lv.w, t[4 * a4 + 3], p1); }
;             float p = quad_sum(p0 + p1);
;             const float ti = (i == j ? 1.f : 0.f) - p;
	v_cndmask_b32_e64 v115, 0, 1.0, vcc
	v_cmp_eq_u32_e32 vcc, 11, v249
	v_writelane_b32 v255, s41, 26
	v_cmp_lt_u32_e64 s[40:41], v27, v3
	v_cndmask_b32_e64 v116, 0, 1.0, vcc
	v_cmp_eq_u32_e32 vcc, 12, v249
	v_writelane_b32 v255, s40, 27
	v_lshl_add_u32 v80, v27, 2, s42
	v_cndmask_b32_e64 v118, 0, 1.0, vcc
	v_cmp_eq_u32_e32 vcc, 13, v249
	v_writelane_b32 v255, s41, 28
	v_cmp_gt_u32_e64 s[40:41], v27, v3
	v_lshlrev_b32_e32 v41, 8, v27
	v_lshlrev_b32_e32 v27, 6, v27
	v_cndmask_b32_e64 v119, 0, 1.0, vcc
	v_cmp_eq_u32_e32 vcc, 14, v249
	v_bitop3_b32 v27, v16, s38, v27 bitop3:0x36
	v_writelane_b32 v255, s40, 29
	v_cndmask_b32_e64 v120, 0, 1.0, vcc
	v_cmp_eq_u32_e32 vcc, 15, v249
	v_lshl_add_u32 v81, v27, 2, s3
	v_or_b32_e32 v27, 9, v15
	v_cndmask_b32_e64 v121, 0, 1.0, vcc
	v_cmp_eq_u32_e32 vcc, 16, v32
	v_writelane_b32 v255, s41, 30
	v_cmp_lt_u32_e64 s[40:41], v27, v3
	v_cndmask_b32_e64 v122, 0, 1.0, vcc
	v_cmp_eq_u32_e32 vcc, 17, v32
	v_writelane_b32 v255, s40, 31
	v_lshl_add_u32 v82, v27, 2, s42
	v_cndmask_b32_e64 v123, 0, 1.0, vcc
	v_cmp_eq_u32_e32 vcc, 18, v32
	v_writelane_b32 v255, s41, 32
	v_cmp_gt_u32_e64 s[40:41], v27, v3
	v_lshlrev_b32_e32 v42, 8, v27
	v_lshlrev_b32_e32 v27, 6, v27
	v_cndmask_b32_e64 v124, 0, 1.0, vcc
	v_cmp_eq_u32_e32 vcc, 19, v32
	v_bitop3_b32 v27, v16, s38, v27 bitop3:0x36
	v_writelane_b32 v255, s40, 33
	v_cndmask_b32_e64 v125, 0, 1.0, vcc
	v_cmp_eq_u32_e32 vcc, 20, v32
	v_lshl_add_u32 v83, v27, 2, s3
	v_or_b32_e32 v27, 10, v15
	v_cndmask_b32_e64 v126, 0, 1.0, vcc
	v_cmp_eq_u32_e32 vcc, 21, v32
	v_writelane_b32 v255, s41, 34
	v_cmp_lt_u32_e64 s[40:41], v27, v3
	v_cndmask_b32_e64 v127, 0, 1.0, vcc
	v_cmp_eq_u32_e32 vcc, 22, v32
	v_writelane_b32 v255, s40, 35
	v_lshl_add_u32 v84, v27, 2, s42
	v_cndmask_b32_e64 v128, 0, 1.0, vcc
	v_cmp_eq_u32_e32 vcc, 23, v32
	v_writelane_b32 v255, s41, 36
	v_cmp_gt_u32_e64 s[40:41], v27, v3
	v_lshlrev_b32_e32 v43, 8, v27
	v_lshlrev_b32_e32 v27, 6, v27
	v_cndmask_b32_e64 v129, 0, 1.0, vcc
	v_cmp_eq_u32_e32 vcc, 24, v32
	v_bitop3_b32 v27, v16, s38, v27 bitop3:0x36
	v_writelane_b32 v255, s40, 37
	v_cndmask_b32_e64 v136, 0, 1.0, vcc
	v_cmp_eq_u32_e32 vcc, 25, v32
	v_lshl_add_u32 v85, v27, 2, s3
	v_or_b32_e32 v27, 11, v15
	v_cndmask_b32_e64 v137, 0, 1.0, vcc
	v_cmp_eq_u32_e32 vcc, 26, v32
	v_writelane_b32 v255, s41, 38
	v_cmp_lt_u32_e64 s[40:41], v27, v3
	v_cndmask_b32_e64 v138, 0, 1.0, vcc
	v_cmp_eq_u32_e32 vcc, 27, v32
	v_writelane_b32 v255, s40, 39
	v_lshl_add_u32 v86, v27, 2, s42
	v_cndmask_b32_e64 v139, 0, 1.0, vcc
	v_cmp_eq_u32_e32 vcc, 28, v32
	v_writelane_b32 v255, s41, 40
	v_cmp_gt_u32_e64 s[40:41], v27, v3
	v_lshlrev_b32_e32 v44, 8, v27
	v_lshlrev_b32_e32 v27, 6, v27
	v_cndmask_b32_e64 v140, 0, 1.0, vcc
	v_cmp_eq_u32_e32 vcc, 29, v32
	v_bitop3_b32 v27, v16, s38, v27 bitop3:0x36
	v_writelane_b32 v255, s40, 41
	v_cndmask_b32_e64 v141, 0, 1.0, vcc
	v_cmp_eq_u32_e32 vcc, 30, v32
	v_lshl_add_u32 v87, v27, 2, s3
	v_or_b32_e32 v27, 16, v15
	v_cndmask_b32_e64 v142, 0, 1.0, vcc
	v_cmp_eq_u32_e32 vcc, 31, v32
	v_writelane_b32 v255, s41, 42
	v_cmp_lt_u32_e64 s[40:41], v27, v3
	v_cndmask_b32_e64 v143, 0, 1.0, vcc
	v_cmp_eq_u32_e32 vcc, 32, v32
	v_writelane_b32 v255, s40, 43
	v_lshl_add_u32 v88, v27, 2, s42
	v_cndmask_b32_e64 v144, 0, 1.0, vcc
	v_cmp_eq_u32_e32 vcc, 33, v32
	v_writelane_b32 v255, s41, 44
	v_cmp_gt_u32_e64 s[40:41], v27, v3
	v_lshlrev_b32_e32 v45, 8, v27
	v_lshlrev_b32_e32 v27, 6, v27
	v_cndmask_b32_e64 v145, 0, 1.0, vcc
	v_cmp_eq_u32_e32 vcc, 34, v32
	v_bitop3_b32 v27, v16, s38, v27 bitop3:0x36
	v_or_b32_e32 v46, 17, v15
	v_cndmask_b32_e64 v146, 0, 1.0, vcc
	v_cmp_eq_u32_e32 vcc, 35, v32
	v_lshl_add_u32 v89, v27, 2, s3
	v_lshlrev_b32_e32 v27, 6, v46
	v_cndmask_b32_e64 v147, 0, 1.0, vcc
	v_cmp_eq_u32_e32 vcc, 36, v32
	v_bitop3_b32 v27, v16, s38, v27 bitop3:0x36
	v_or_b32_e32 v48, 18, v15
	v_cndmask_b32_e64 v148, 0, 1.0, vcc
	v_cmp_eq_u32_e32 vcc, 37, v32
	v_lshl_add_u32 v91, v27, 2, s3
	v_lshlrev_b32_e32 v27, 6, v48
	v_cndmask_b32_e64 v149, 0, 1.0, vcc
	v_cmp_eq_u32_e32 vcc, 38, v32
	v_bitop3_b32 v27, v16, s38, v27 bitop3:0x36
	v_or_b32_e32 v230, 19, v15
	v_cndmask_b32_e64 v150, 0, 1.0, vcc
	v_cmp_eq_u32_e32 vcc, 39, v32
	v_lshl_add_u32 v93, v27, 2, s3
	v_lshlrev_b32_e32 v27, 6, v230
	v_cndmask_b32_e64 v151, 0, 1.0, vcc
	v_cmp_eq_u32_e32 vcc, 40, v32
	v_bitop3_b32 v27, v16, s38, v27 bitop3:0x36
	v_or_b32_e32 v231, 24, v15
	v_cndmask_b32_e64 v152, 0, 1.0, vcc
	v_cmp_eq_u32_e32 vcc, 41, v32
	v_lshl_add_u32 v95, v27, 2, s3
	v_lshlrev_b32_e32 v27, 6, v231
	v_cndmask_b32_e64 v153, 0, 1.0, vcc
	v_cmp_eq_u32_e32 vcc, 42, v32
	v_bitop3_b32 v27, v16, s38, v27 bitop3:0x36
	v_or_b32_e32 v232, 25, v15
	v_cndmask_b32_e64 v154, 0, 1.0, vcc
	v_cmp_eq_u32_e32 vcc, 43, v32
	v_lshl_add_u32 v97, v27, 2, s3
	v_lshlrev_b32_e32 v27, 6, v232
	v_cndmask_b32_e64 v155, 0, 1.0, vcc
	v_cmp_eq_u32_e32 vcc, 44, v32
	v_bitop3_b32 v27, v16, s38, v27 bitop3:0x36
	v_or_b32_e32 v233, 26, v15
	v_cndmask_b32_e64 v156, 0, 1.0, vcc
	v_cmp_eq_u32_e32 vcc, 45, v32
	v_lshl_add_u32 v99, v27, 2, s3
	v_lshlrev_b32_e32 v27, 6, v233
	v_cndmask_b32_e64 v157, 0, 1.0, vcc
	v_cmp_eq_u32_e32 vcc, 46, v32
	v_lshl_add_u32 v72, v15, 2, s42
	v_cmp_lt_u32_e64 s[6:7], v15, v3
	v_mul_u32_u24_e32 v36, 0x90, v15
	v_lshlrev_b32_e32 v37, 8, v15
	v_bitop3_b32 v27, v16, s38, v27 bitop3:0x36
	v_or_b32_e32 v15, 27, v15
	v_cndmask_b32_e64 v158, 0, 1.0, vcc
	v_cmp_eq_u32_e32 vcc, 47, v32
	v_lshl_add_u32 v101, v27, 2, s3
	v_lshlrev_b32_e32 v27, 6, v15
	v_cndmask_b32_e64 v159, 0, 1.0, vcc
	v_cmp_eq_u32_e32 vcc, 48, v32
	v_bitop3_b32 v26, v7, 63, 3 bitop3:0x6c
	v_bitop3_b32 v16, v16, s38, v27 bitop3:0x36
	v_cndmask_b32_e64 v160, 0, 1.0, vcc
; #define LAS __attribute__((address_space(3)))
; __device__ __forceinline__ void gdn_prep_phase(LAS unsigned char* lds, const GdnPrepArgs& A, int bid, int G, const unsigned char* zero_page) {
;     ...
;         const int dir = w >> 2, li = (w & 3) * 64 + lane, j = li >> 2, q = li & 3;
;         const LAS float* LP = (const LAS float*)(lds + (dir ? L_LPB : L_LPF)) + q * 16;
;         float t[16];
; #pragma unroll
;         for (int a = 0; a < 16; ++a) t[a] = 0.f;
;         f32x4 lq[3][4];
;     ...
;         SOLVE_LD(0); SOLVE_LD(1);
; #pragma unroll
;         for (int i = 0; i < 64; ++i) {
;             if (i + 2 < 48) SOLVE_LD(i + 2);
;             else if (i + 1 >= 48 && i + 1 < 64) SOLVE_LD(i + 1);
;             float p0 = 0.f, p1 = 0.f;
; #pragma unroll
;             for (int a4 = 0; a4 < (i + 15) / 16; ++a4) { const f32x4 lv = lq[i % 3][a4];
;                 p0 = __builtin_fmaf(lv.x, t[4 * a4], p0); p1 = __builtin_fmaf(lv.y, t[4 * a4 + 1], p1); p0 = __builtin_fmaf(lv.z, t[4 * a4 + 2], p0); p1 = __builtin_fmaf(lv.w, t[4 * a4 + 3], p1); }
;             float p = quad_sum(p0 + p1);
;             const float ti = (i == j ? 1.f : 0.f) - p;
;             if (q == (i & 3)) t[i >> 2] = ti;
;             if ((i & 7) == 3 && !(pflg & 64)) {
;                 constexpr int kk = 0; const int k8 = i >> 3, b = w + 8 * (k8 & 1); v4u f; int off; (void)kk;
;                 if (k8 < 2)      { f = frag16_rm(lds + L_KN, QS_, b >> 2, b & 3, lane); off = B_KA + b * 1024; }
;                 else if (k8 < 4) { f = frag16_rm(lds + L_QN, QS_, b >> 2, b & 3, lane); off = B_QA + b * 1024; }
;                 else if (k8 < 6) { f = frag16_tr(lds + L_KN, QS_, b >> 1, b & 1, lane); off = B_KT + b * 1024; }
;                 else             { f = frag16_rm(lds + (k8 == 6 ? L_AF : L_AB), AS_, w >> 1, w & 1, lane); off = (k8 == 6 ? B_AF : B_AB) + w * 1024; }
;                 *(v4u*)(blob + off + lane * 16) = f; }
;             __builtin_amdgcn_sched_barrier(0);
;         }
;     ...
;         const LAS float* sc = (const LAS float*)(lds + L_SC);
;         if (dir == 0) { const float bj = sc[128 + j];
; #pragma unroll
;             for (int a = 0; a < 16; ++a) *(LAS unsigned short*)(lds + L_TBF + (4 * a + q) * AS_ + j * 2) = (unsigned short)(pkbf(t[a] * bj, 0.f) & 0xffffu);
;         } else { const int jo = 63 - j; const float bj = sc[192 + jo];
; #pragma unroll
	v_cmp_eq_u32_e32 vcc, 49, v32
	v_lshl_add_u32 v103, v16, 2, s3
	v_mul_u32_u24_e32 v16, 0x90, v26
	v_bitop3_b32 v26, v7, 55, 3 bitop3:0x6c
	v_cndmask_b32_e64 v161, 0, 1.0, vcc
	v_cmp_eq_u32_e32 vcc, 50, v32
	v_mul_u32_u24_e32 v210, 0x90, v26
	v_bitop3_b32 v26, v7, 51, 3 bitop3:0x6c
	v_cndmask_b32_e64 v162, 0, 1.0, vcc
	v_cmp_eq_u32_e32 vcc, 51, v32
	v_mul_u32_u24_e32 v211, 0x90, v26
	v_bitop3_b32 v26, v7, 47, 3 bitop3:0x6c
	v_cndmask_b32_e64 v163, 0, 1.0, vcc
	v_cmp_eq_u32_e32 vcc, 52, v32
	v_mul_u32_u24_e32 v212, 0x90, v26
	v_bitop3_b32 v26, v7, 43, 3 bitop3:0x6c
	v_readlane_b32 s38, v251, 39
	v_cndmask_b32_e64 v173, 0, 1.0, vcc
	v_cmp_eq_u32_e32 vcc, 53, v32
	v_add_u32_e32 v54, 0, v130
	v_mul_u32_u24_e32 v213, 0x90, v26
	v_bitop3_b32 v26, v7, 39, 3 bitop3:0x6c
	v_lshlrev_b32_e32 v130, 3, v18
	v_readlane_b32 s39, v251, 40
	v_cndmask_b32_e64 v174, 0, 1.0, vcc
	v_cmp_eq_u32_e32 vcc, 54, v32
	v_writelane_b32 v255, s40, 45
	v_mul_u32_u24_e32 v214, 0x90, v26
	v_bitop3_b32 v26, v7, 35, 3 bitop3:0x6c
	v_lshl_add_u64 v[28:29], s[38:39], 0, v[130:131]
	v_readlane_b32 s38, v251, 41
	v_cndmask_b32_e64 v175, 0, 1.0, vcc
	v_cmp_eq_u32_e32 vcc, 55, v32
	v_writelane_b32 v255, s41, 46
	v_mul_u32_u24_e32 v215, 0x90, v26
	v_bitop3_b32 v26, v7, 31, 3 bitop3:0x6c
	v_readlane_b32 s39, v251, 42
	s_add_i32 s41, s34, 8
	v_cndmask_b32_e64 v176, 0, 1.0, vcc
	v_cmp_eq_u32_e32 vcc, 56, v32
	v_mul_u32_u24_e32 v216, 0x90, v26
	v_bitop3_b32 v26, v7, 27, 3 bitop3:0x6c
	v_lshl_add_u64 v[30:31], s[38:39], 0, v[130:131]
	s_lshl_b32 s38, s41, 2
	v_cndmask_b32_e64 v177, 0, 1.0, vcc
	v_cmp_eq_u32_e32 vcc, 57, v32
	v_mul_u32_u24_e32 v217, 0x90, v26
	v_bitop3_b32 v26, v7, 23, 3 bitop3:0x6c
	v_readlane_b32 s68, v250, 10
	s_and_b32 s38, s38, 0xffffff0
	v_cndmask_b32_e64 v178, 0, 1.0, vcc
	v_cmp_eq_u32_e32 vcc, 58, v32
	v_mul_u32_u24_e32 v218, 0x90, v26
	v_bitop3_b32 v26, v7, 19, 3 bitop3:0x6c
	v_readlane_b32 s72, v250, 14
	s_lshl_b32 s40, s34, 2
	v_or_b32_e32 v117, s38, v57
	s_lshl_b32 s38, s41, 10
	v_cndmask_b32_e64 v179, 0, 1.0, vcc
	v_cmp_eq_u32_e32 vcc, 59, v32
	s_lshl_b32 s41, s41, 4
	s_lshl_b32 s2, s34, 10
	v_mul_u32_u24_e32 v219, 0x90, v26
	v_bitop3_b32 v26, v7, 15, 3 bitop3:0x6c
	s_and_b32 s3, s40, 0xffffff0
	v_cndmask_b32_e64 v180, 0, 1.0, vcc
	v_cmp_eq_u32_e32 vcc, 60, v32
	s_and_b32 s72, s41, 0xffffffe0
	s_add_i32 s41, s34, -8
	v_mul_u32_u24_e32 v220, 0x90, v26
	v_bitop3_b32 v26, v7, 11, 3 bitop3:0x6c
	v_or_b32_e32 v108, s3, v57
	s_ashr_i32 s3, s2, 31
	v_cndmask_b32_e64 v181, 0, 1.0, vcc
	v_cmp_eq_u32_e32 vcc, 61, v32
	v_writelane_b32 v255, s41, 47
	v_lshrrev_b32_e32 v10, 4, v18
	v_bitop3_b32 v17, v7, 59, 3 bitop3:0x6c
	v_mul_u32_u24_e32 v221, 0x90, v26
	v_bitop3_b32 v26, v7, 7, 3 bitop3:0x6c
	v_bitop3_b32 v7, v7, 3, v7 bitop3:0xc
	v_readlane_b32 s70, v250, 12
	v_cndmask_b32_e64 v182, 0, 1.0, vcc
	v_cmp_eq_u32_e32 vcc, 62, v32
	v_writelane_b32 v255, s2, 48
	v_lshlrev_b32_e32 v22, 4, v18
	v_add_u32_e32 v65, s42, v4
	v_or_b32_e32 v2, 64, v18
	v_or_b32_e32 v4, 0x80, v18
	v_or_b32_e32 v6, 0xc0, v18
	v_lshlrev_b32_e32 v47, 8, v46
	v_lshlrev_b32_e32 v49, 8, v48
	v_lshlrev_b32_e32 v203, 8, v230
	v_lshlrev_b32_e32 v204, 8, v231
	v_lshlrev_b32_e32 v205, 8, v232
	v_lshlrev_b32_e32 v206, 8, v233
	v_lshlrev_b32_e32 v207, 8, v15
	v_mul_u32_u24_e32 v17, 0x90, v17
	v_mul_u32_u24_e32 v222, 0x90, v26
	v_mul_u32_u24_e32 v7, 0x90, v7
	v_mul_u32_u24_e32 v224, 0x90, v5
	v_readlane_b32 s69, v250, 11
	v_readlane_b32 s71, v250, 13
	v_readlane_b32 s74, v250, 16
	v_readlane_b32 s75, v250, 17
	v_readlane_b32 s76, v250, 18
	v_readlane_b32 s77, v250, 19
	v_readlane_b32 s78, v250, 20
	v_readlane_b32 s79, v250, 21
	v_readlane_b32 s80, v250, 22
	v_readlane_b32 s81, v250, 23
	s_movk_i32 s70, 0x110
	v_cndmask_b32_e64 v183, 0, 1.0, vcc
	v_cmp_eq_u32_e32 vcc, 63, v32
	v_or_b32_e32 v189, s40, v10
	v_writelane_b32 v255, s3, 49
	s_add_i32 s40, s2, 0
	v_lshlrev_b32_e32 v20, 8, v18
	v_and_b32_e32 v24, 0xf0, v22
	v_mov_b32_e32 v25, v131
	v_lshl_add_u32 v55, v3, 2, s42
	v_mov_b32_e32 v23, v131
	v_lshl_add_u32 v66, v2, 2, s42
	v_lshl_add_u32 v67, v4, 2, s42
	v_lshl_add_u32 v68, v6, 2, s42
	v_lshlrev_b32_e32 v70, 2, v21
	s_mulk_i32 s53, 0x110
	v_add_u32_e32 v71, 0x11000, v54
	v_mov_b32_e32 v21, v131
	v_lshl_add_u32 v90, v46, 2, s42
	v_lshl_add_u32 v92, v48, 2, s42
	v_lshl_add_u32 v94, v230, 2, s42
	v_lshl_add_u32 v96, v231, 2, s42
; #define LAS __attribute__((address_space(3)))
; __device__ __forceinline__ void gdn_prep_phase(LAS unsigned char* lds, const GdnPrepArgs& A, int bid, int G, const unsigned char* zero_page) {
;     ...
;         const LAS unsigned char* ia = lds + (which ? L_QN : L_KN) + (32 * rt + r) * QS_ + 16 * hh;
;         const LAS unsigned char* ib = lds + L_KN + (32 * ct + r) * QS_ + 16 * hh;
;         f32x16 acc = zero16();
; #pragma unroll
;         for (int ks = 0; ks < 8; ++ks) acc = MFMA32(*(const LAS bf16x8*)(ia + 32 * ks), *(const LAS bf16x8*)(ib + 32 * ks), acc);
;         const LAS float* sc = (const LAS float*)(lds + L_SC);
;         const int j = 32 * ct + r; const float gfj = sc[j], gbj = sc[64 + j];
; #pragma unroll
;         for (int reg = 0; reg < 16; ++reg) {
;             const int i = 32 * rt + (reg & 3) + 8 * (reg >> 2) + 4 * hh; const float val = acc[reg];
;             const float ef = __expf(sc[i] - gfj), eb = __expf(sc[64 + i] - gbj);
;             if (which == 0) {
;                 const float lf = (i > j) ? sc[128 + i] * val * ef : 0.f, lb = (i < j) ? sc[192 + i] * val * eb : 0.f;
;                 ((LAS float*)(lds + L_LPF))[i * 64 + (j & 3) * 16 + (j >> 2)] = lf;
;                 const int i2 = 63 - i, j2 = 63 - j;
;                 ((LAS float*)(lds + L_LPB))[i2 * 64 + (j2 & 3) * 16 + (j2 >> 2)] = lb;
;             } else {
;                 const float af = (i >= j) ? QSCALE * val * ef : 0.f, ab = (i <= j) ? QSCALE * val * eb : 0.f;
;                 *(LAS unsigned short*)(lds + L_AF + i * AS_ + j * 2) = (unsigned short)(pkbf(af, 0.f) & 0xffffu);
;                 *(LAS unsigned short*)(lds + L_AB + i * AS_ + j * 2) = (unsigned short)(pkbf(ab, 0.f) & 0xffffu);
;     ...
;         const int dir = w >> 2, li = (w & 3) * 64 + lane, j = li >> 2, q = li & 3;
;         const LAS float* LP = (const LAS float*)(lds + (dir ? L_LPB : L_LPF)) + q * 16;
;         float t[16];
; #pragma unroll
;         for (int a = 0; a < 16; ++a) t[a] = 0.f;
;         f32x4 lq[3][4];
;     ...
;         SOLVE_LD(0); SOLVE_LD(1);
; #pragma unroll
;         for (int i = 0; i < 64; ++i) {
;             if (i + 2 < 48) SOLVE_LD(i + 2);
;             else if (i + 1 >= 48 && i + 1 < 64) SOLVE_LD(i + 1);
;             float p0 = 0.f, p1 = 0.f;
; #pragma unroll
;             for (int a4 = 0; a4 < (i + 15) / 16; ++a4) { const f32x4 lv = lq[i % 3][a4];
	v_lshl_add_u32 v98, v232, 2, s42
	v_lshl_add_u32 v100, v233, 2, s42
	v_lshl_add_u32 v102, v15, 2, s42
	v_lshl_add_u64 v[26:27], s[74:75], 0, v[130:131]
	v_mul_lo_u32 v108, v108, s70
	v_mul_lo_u32 v117, v117, s70
	s_ashr_i32 s39, s38, 31
	v_cndmask_b32_e64 v184, 0, 1.0, vcc
	s_and_b32 s71, s67, 0xffffffe0
	v_add_u32_e32 v185, 0x1d800, v33
	v_add_u32_e32 v186, 0x1d820, v33
	v_add_u32_e32 v187, 0x1fc00, v33
	v_add_u32_e32 v188, 0x1fc20, v33
	v_writelane_b32 v255, s40, 50
	v_add_u32_e32 v190, v11, v12
	v_add_u32_e32 v191, v14, v12
	v_add_u32_e32 v192, v13, v37
	v_add_u32_e32 v193, v13, v38
	v_add_u32_e32 v194, v13, v39
	v_add_u32_e32 v195, v13, v40
	v_add_u32_e32 v196, v13, v41
	v_add_u32_e32 v197, v13, v42
	v_add_u32_e32 v198, v13, v43
	v_add_u32_e32 v199, v13, v44
	v_add_u32_e32 v200, v13, v45
	v_add_u32_e32 v201, v13, v47
	v_add_u32_e32 v202, v13, v49
	v_add_u32_e32 v203, v13, v203
	v_add_u32_e32 v204, v13, v204
	v_add_u32_e32 v205, v13, v205
	v_add_u32_e32 v206, v13, v206
	v_add_u32_e32 v207, v13, v207
	v_add_u32_e32 v208, v34, v16
	v_add_u32_e32 v209, v34, v17
	v_add_u32_e32 v210, v34, v210
	v_add_u32_e32 v211, v34, v211
	v_add_u32_e32 v212, v34, v212
	v_add_u32_e32 v213, v34, v213
	v_add_u32_e32 v214, v34, v214
	v_add_u32_e32 v215, v34, v215
	v_add_u32_e32 v216, v34, v216
	v_add_u32_e32 v217, v34, v217
	v_add_u32_e32 v218, v34, v218
	v_add_u32_e32 v219, v34, v219
	v_add_u32_e32 v220, v34, v220
	v_add_u32_e32 v221, v34, v221
	v_add_u32_e32 v222, v34, v222
	v_add_u32_e32 v223, v34, v7
	v_add_u32_e32 v224, v35, v224
	v_lshlrev_b32_e32 v225, 2, v2
	v_lshlrev_b32_e32 v226, 2, v4
	v_lshlrev_b32_e32 v227, 2, v6
	v_add_u32_e32 v228, v8, v36
	v_add_u32_e32 v229, v9, v36
	s_mov_b32 s56, s85
	v_cmp_lt_u32_e64 s[74:75], v46, v3
	v_cmp_gt_u32_e64 s[76:77], v46, v3
	v_cmp_lt_u32_e64 s[58:59], v48, v3
	v_cmp_gt_u32_e64 s[60:61], v48, v3
	v_cmp_lt_u32_e64 s[62:63], v230, v3
	v_cmp_gt_u32_e64 s[64:65], v230, v3
	v_cmp_lt_u32_e64 s[84:85], v231, v3
	v_cmp_gt_u32_e64 s[78:79], v231, v3
	v_cmp_lt_u32_e64 s[80:81], v232, v3
	v_cmp_gt_u32_e64 s[26:27], v232, v3
	v_cmp_lt_u32_e64 s[28:29], v233, v3
	v_cmp_gt_u32_e64 s[30:31], v233, v3
	v_cmp_lt_u32_e64 s[24:25], v15, v3
	v_cmp_gt_u32_e64 s[36:37], v15, v3
	v_cmp_eq_u32_e64 s[86:87], 0, v5
	v_cmp_eq_u32_e64 s[88:89], 1, v5
	v_cmp_eq_u32_e64 s[90:91], 2, v5
	v_cmp_eq_u32_e64 s[92:93], 3, v5
	s_mov_b32 s68, 0x55555556
	s_movk_i32 s69, 0x800
	v_readlane_b32 s73, v250, 15
	v_readlane_b32 s82, v250, 24
	v_readlane_b32 s83, v250, 25
	s_mul_i32 s46, s101, 0x1010
	s_mul_i32 s47, s100, 0x2400
	s_add_i32 s47, s47, 0x22000
	s_lshl_b32 s48, s101, 11
	s_lshl_b32 s49, s100, 14
	s_add_i32 s49, s49, 0x15800
	s_lshl_b32 s50, s100, 1
	s_sub_i32 s50, 1, s50
	s_mul_i32 s51, s100, 0x47ee
	s_add_i32 s51, s51, 0x22000
	s_mul_i32 s54, s100, 508
	s_add_i32 s54, s54, 0x15600
	s_lshl_b32 s55, s101, 4
	s_add_i32 s1, s47, s48
	s_add_i32 s32, s1, 0x400
	s_add_i32 s2, s49, s46
	s_add_i32 s2, s2, 0x1000
	s_mul_i32 s3, s50, 0x240
	s_mul_i32 s57, s50, 0x90
	v_mbcnt_lo_u32_b32 v2, -1, 0
	v_mbcnt_hi_u32_b32 v2, -1, v2
	v_and_b32_e32 v3, 3, v2
	v_lshrrev_b32_e32 v4, 2, v2
	v_add_u32_e32 v173, s46, v56
	v_lshlrev_b32_e32 v236, 2, v3
	v_lshl_or_b32 v236, v4, 6, v236
	v_add_u32_e32 v174, s1, v236
	v_lshlrev_b32_e32 v236, 2, v4
	v_lshl_or_b32 v236, v3, 6, v236
	v_add_u32_e32 v175, s32, v236
	v_and_b32_e32 v237, 15, v2
	v_lshrrev_b32_e32 v249, 4, v2
	v_lshlrev_b32_e32 v236, 2, v249
	v_lshl_or_b32 v236, v237, 8, v236
	v_add_u32_e32 v176, s2, v236
	v_add_u32_e32 v177, 0x1000, v176
	v_add_u32_e32 v178, 0x1000, v177
	v_lshlrev_b32_e32 v236, 4, v249
	v_lshl_or_b32 v236, v237, 6, v236
	v_add_u32_e32 v180, s1, v236
	v_add_u32_e32 v179, 0x400, v180
	v_add_u32_e32 v236, s55, v4
	v_lshlrev_b32_e32 v130, 1, v236
	v_mul_u32_u24_e32 v3, 0x90, v3
	v_add_u32_e32 v130, v130, v3
	v_mul_lo_u32 v130, v130, s50
	v_add_u32_e32 v181, s51, v130
	v_lshlrev_b32_e32 v236, 2, v236
	v_mul_lo_u32 v236, v236, s50
	v_add_u32_e32 v224, s54, v236
	v_mov_b32_e32 v182, s3
	v_mov_b32_e32 v184, s57
	v_lshl_add_u32 v236, v249, 2, s55
	v_mul_u32_u24_e32 v236, 0x90, v236
	v_add_u32_e32 v130, s55, v237
	v_lshl_add_u32 v236, v130, 1, v236
	v_mul_lo_u32 v236, v236, s50
	v_add_u32_e32 v183, s51, v236
	v_lshlrev_b32_e32 v130, 2, v130
	v_mul_lo_u32 v130, v130, s50
	v_add_u32_e32 v246, s54, v130
	s_waitcnt vmcnt(0)
	s_nop 0
	s_branch .LBB0_201

; #define LAS __attribute__((address_space(3)))
; #define MFMA32(a, b, c) __builtin_amdgcn_mfma_f32_32x32x16_bf16((a), (b), (c), 0, 0, 0)
; __device__ __forceinline__ void gdn_prep_phase(LAS unsigned char* lds, const GdnPrepArgs& A, int bid, int G, const unsigned char* zero_page) {
;     ...
;         const LAS unsigned char* ia = lds + (which ? L_QN : L_KN) + (32 * rt + r) * QS_ + 16 * hh;
;         const LAS unsigned char* ib = lds + L_KN + (32 * ct + r) * QS_ + 16 * hh;
;         f32x16 acc = zero16();
; #pragma unroll
;         for (int ks = 0; ks < 8; ++ks) acc = MFMA32(*(const LAS bf16x8*)(ia + 32 * ks), *(const LAS bf16x8*)(ib + 32 * ks), acc);
;         const LAS float* sc = (const LAS float*)(lds + L_SC);
;         const int j = 32 * ct + r; const float gfj = sc[j], gbj = sc[64 + j];
; #pragma unroll
;         for (int reg = 0; reg < 16; ++reg) {
;             const int i = 32 * rt + (reg & 3) + 8 * (reg >> 2) + 4 * hh; const float val = acc[reg];
;             const float ef = __expf(sc[i] - gfj), eb = __expf(sc[64 + i] - gbj);
.LBB0_209:
	s_mov_b32 s98, 0x3fb8aa3b
	ds_read2st64_b32 v[44:45], v55 offset1:1
	ds_read2st64_b32 v[136:137], v72 offset1:1
	ds_read2st64_b32 v[138:139], v74 offset1:1
	ds_read2st64_b32 v[140:141], v76 offset1:1
	ds_read2st64_b32 v[142:143], v78 offset1:1
	ds_read2st64_b32 v[144:145], v80 offset1:1
	ds_read2st64_b32 v[146:147], v82 offset1:1
	ds_read2st64_b32 v[148:149], v84 offset1:1
	ds_read2st64_b32 v[150:151], v86 offset1:1
	ds_read2st64_b32 v[152:153], v88 offset1:1
	ds_read2st64_b32 v[154:155], v90 offset1:1
	ds_read2st64_b32 v[156:157], v92 offset1:1
	ds_read2st64_b32 v[158:159], v94 offset1:1
	ds_read2st64_b32 v[160:161], v96 offset1:1
	ds_read2st64_b32 v[162:163], v98 offset1:1
	ds_read2st64_b32 v[230:231], v100 offset1:1
	ds_read2st64_b32 v[232:233], v102 offset1:1
	ds_read2st64_b32 v[234:235], v72 offset0:2 offset1:3
	ds_read2st64_b32 v[236:237], v74 offset0:2 offset1:3
	ds_read2st64_b32 v[238:239], v76 offset0:2 offset1:3
	ds_read2st64_b32 v[240:241], v78 offset0:2 offset1:3
	ds_read2st64_b32 v[242:243], v80 offset0:2 offset1:3
	ds_read2st64_b32 v[244:245], v82 offset0:2 offset1:3
	ds_read2st64_b32 v[248:249], v84 offset0:2 offset1:3
	ds_read2st64_b32 v[208:209], v86 offset0:2 offset1:3
	ds_read2st64_b32 v[210:211], v88 offset0:2 offset1:3
	ds_read2st64_b32 v[212:213], v90 offset0:2 offset1:3
	ds_read2st64_b32 v[214:215], v92 offset0:2 offset1:3
	ds_read2st64_b32 v[216:217], v94 offset0:2 offset1:3
	ds_read2st64_b32 v[218:219], v96 offset0:2 offset1:3
	ds_read2st64_b32 v[220:221], v98 offset0:2 offset1:3
	ds_read2st64_b32 v[46:47], v100 offset0:2 offset1:3
	ds_read2st64_b32 v[48:49], v102 offset0:2 offset1:3
	ds_read_b128 v[32:35], v190
	ds_read_b128 v[36:39], v191
	s_waitcnt lgkmcnt(0)
	v_mfma_f32_32x32x16_bf16 v[2:17], v[32:35], v[36:39], 0
	v_pk_add_f32 v[136:137], v[136:137], v[44:45] neg_lo:[0,1] neg_hi:[0,1]
	v_pk_add_f32 v[138:139], v[138:139], v[44:45] neg_lo:[0,1] neg_hi:[0,1]
	v_pk_mul_f32 v[136:137], v[136:137], s[98:99] op_sel_hi:[1,0]
	v_pk_mul_f32 v[138:139], v[138:139], s[98:99] op_sel_hi:[1,0]
	v_exp_f32_e32 v136, v136
	v_exp_f32_e32 v137, v137
	v_exp_f32_e32 v138, v138
	v_exp_f32_e32 v139, v139
	ds_read_b128 v[32:35], v190 offset:32
	ds_read_b128 v[36:39], v191 offset:32
	s_waitcnt lgkmcnt(0)
	v_mfma_f32_32x32x16_bf16 v[2:17], v[32:35], v[36:39], v[2:17]
	v_pk_add_f32 v[140:141], v[140:141], v[44:45] neg_lo:[0,1] neg_hi:[0,1]
	v_pk_add_f32 v[142:143], v[142:143], v[44:45] neg_lo:[0,1] neg_hi:[0,1]
	v_pk_mul_f32 v[140:141], v[140:141], s[98:99] op_sel_hi:[1,0]
	v_pk_mul_f32 v[142:143], v[142:143], s[98:99] op_sel_hi:[1,0]
	v_exp_f32_e32 v140, v140
	v_exp_f32_e32 v141, v141
	v_exp_f32_e32 v142, v142
	v_exp_f32_e32 v143, v143
	ds_read_b128 v[32:35], v190 offset:64
	ds_read_b128 v[36:39], v191 offset:64
	s_waitcnt lgkmcnt(0)
	v_mfma_f32_32x32x16_bf16 v[2:17], v[32:35], v[36:39], v[2:17]
	v_pk_add_f32 v[144:145], v[144:145], v[44:45] neg_lo:[0,1] neg_hi:[0,1]
	v_pk_add_f32 v[146:147], v[146:147], v[44:45] neg_lo:[0,1] neg_hi:[0,1]
	v_pk_mul_f32 v[144:145], v[144:145], s[98:99] op_sel_hi:[1,0]
	v_pk_mul_f32 v[146:147], v[146:147], s[98:99] op_sel_hi:[1,0]
	v_exp_f32_e32 v144, v144
	v_exp_f32_e32 v145, v145
	v_exp_f32_e32 v146, v146
	v_exp_f32_e32 v147, v147
	ds_read_b128 v[32:35], v190 offset:96
	ds_read_b128 v[36:39], v191 offset:96
	s_waitcnt lgkmcnt(0)
	v_mfma_f32_32x32x16_bf16 v[2:17], v[32:35], v[36:39], v[2:17]
	v_pk_add_f32 v[148:149], v[148:149], v[44:45] neg_lo:[0,1] neg_hi:[0,1]
	v_pk_add_f32 v[150:151], v[150:151], v[44:45] neg_lo:[0,1] neg_hi:[0,1]
	v_pk_mul_f32 v[148:149], v[148:149], s[98:99] op_sel_hi:[1,0]
	v_pk_mul_f32 v[150:151], v[150:151], s[98:99] op_sel_hi:[1,0]
	v_exp_f32_e32 v148, v148
	v_exp_f32_e32 v149, v149
	v_exp_f32_e32 v150, v150
	v_exp_f32_e32 v151, v151
	ds_read_b128 v[32:35], v190 offset:128
	ds_read_b128 v[36:39], v191 offset:128
	s_waitcnt lgkmcnt(0)
	v_mfma_f32_32x32x16_bf16 v[2:17], v[32:35], v[36:39], v[2:17]
	v_pk_add_f32 v[152:153], v[152:153], v[44:45] neg_lo:[0,1] neg_hi:[0,1]
	v_pk_add_f32 v[154:155], v[154:155], v[44:45] neg_lo:[0,1] neg_hi:[0,1]
	v_pk_mul_f32 v[152:153], v[152:153], s[98:99] op_sel_hi:[1,0]
	v_pk_mul_f32 v[154:155], v[154:155], s[98:99] op_sel_hi:[1,0]
	v_exp_f32_e32 v152, v152
	v_exp_f32_e32 v153, v153
	v_exp_f32_e32 v154, v154
	v_exp_f32_e32 v155, v155
	ds_read_b128 v[32:35], v190 offset:160
	ds_read_b128 v[36:39], v191 offset:160
	s_waitcnt lgkmcnt(0)
	v_mfma_f32_32x32x16_bf16 v[2:17], v[32:35], v[36:39], v[2:17]
	v_pk_add_f32 v[156:157], v[156:157], v[44:45] neg_lo:[0,1] neg_hi:[0,1]
	v_pk_add_f32 v[158:159], v[158:159], v[44:45] neg_lo:[0,1] neg_hi:[0,1]
	v_pk_mul_f32 v[156:157], v[156:157], s[98:99] op_sel_hi:[1,0]
	v_pk_mul_f32 v[158:159], v[158:159], s[98:99] op_sel_hi:[1,0]
	v_exp_f32_e32 v156, v156
	v_exp_f32_e32 v157, v157
	v_exp_f32_e32 v158, v158
	v_exp_f32_e32 v159, v159
	ds_read_b128 v[32:35], v190 offset:192
	ds_read_b128 v[36:39], v191 offset:192
	s_waitcnt lgkmcnt(0)
	v_mfma_f32_32x32x16_bf16 v[2:17], v[32:35], v[36:39], v[2:17]
	v_pk_add_f32 v[160:161], v[160:161], v[44:45] neg_lo:[0,1] neg_hi:[0,1]
	v_pk_add_f32 v[162:163], v[162:163], v[44:45] neg_lo:[0,1] neg_hi:[0,1]
	v_pk_mul_f32 v[160:161], v[160:161], s[98:99] op_sel_hi:[1,0]
	v_pk_mul_f32 v[162:163], v[162:163], s[98:99] op_sel_hi:[1,0]
	v_exp_f32_e32 v160, v160
	v_exp_f32_e32 v161, v161
	v_exp_f32_e32 v162, v162
	v_exp_f32_e32 v163, v163
	ds_read_b128 v[32:35], v190 offset:224
	ds_read_b128 v[36:39], v191 offset:224
	s_waitcnt lgkmcnt(0)
	v_mfma_f32_32x32x16_bf16 v[2:17], v[32:35], v[36:39], v[2:17]
	v_pk_add_f32 v[230:231], v[230:231], v[44:45] neg_lo:[0,1] neg_hi:[0,1]
	v_pk_add_f32 v[232:233], v[232:233], v[44:45] neg_lo:[0,1] neg_hi:[0,1]
	v_pk_mul_f32 v[230:231], v[230:231], s[98:99] op_sel_hi:[1,0]
	v_pk_mul_f32 v[232:233], v[232:233], s[98:99] op_sel_hi:[1,0]
	v_exp_f32_e32 v230, v230
	v_exp_f32_e32 v231, v231
	v_exp_f32_e32 v232, v232
	v_exp_f32_e32 v233, v233
	v_mbcnt_lo_u32_b32 v222, -1, 0
	v_mbcnt_hi_u32_b32 v222, -1, v222
	v_readfirstlane_b32 s99, v0
	v_and_b32_e32 v223, 31, v222
	v_lshrrev_b32_e32 v222, 5, v222
	s_lshr_b32 s99, s99, 6
	s_and_b32 s46, s99, 1
	s_bfe_u32 s47, s99, 0x10001
	s_sub_i32 s46, s46, s47
	s_lshl_b32 s46, s46, 5
	v_lshlrev_b32_e32 v222, 2, v222
	v_sub_u32_e32 v222, v223, v222
	v_add_u32_e32 v222, s46, v222
	s_and_b64 vcc, exec, s[4:5]
	s_cbranch_vccz .Ls3_lpath
; #define LAS __attribute__((address_space(3)))
; __device__ __forceinline__ unsigned pkbf(float a, float b) { bf16x2_t v = __builtin_convertvector((f32x2_t){a, b}, bf16x2_t); return __builtin_bit_cast(unsigned, v); }
; __device__ __forceinline__ void gdn_prep_phase(LAS unsigned char* lds, const GdnPrepArgs& A, int bid, int G, const unsigned char* zero_page) {
;     ...
; #pragma unroll
;         for (int reg = 0; reg < 16; ++reg) {
;             const int i = 32 * rt + (reg & 3) + 8 * (reg >> 2) + 4 * hh; const float val = acc[reg];
;             const float ef = __expf(sc[i] - gfj), eb = __expf(sc[64 + i] - gbj);
;             if (which == 0) {
;                 const float lf = (i > j) ? sc[128 + i] * val * ef : 0.f, lb = (i < j) ? sc[192 + i] * val * eb : 0.f;
;                 ((LAS float*)(lds + L_LPF))[i * 64 + (j & 3) * 16 + (j >> 2)] = lf;
;                 const int i2 = 63 - i, j2 = 63 - j;
;                 ((LAS float*)(lds + L_LPB))[i2 * 64 + (j2 & 3) * 16 + (j2 >> 2)] = lb;
;             } else {
;                 const float af = (i >= j) ? QSCALE * val * ef : 0.f, ab = (i <= j) ? QSCALE * val * eb : 0.f;
;                 *(LAS unsigned short*)(lds + L_AF + i * AS_ + j * 2) = (unsigned short)(pkbf(af, 0.f) & 0xffffu);
;                 *(LAS unsigned short*)(lds + L_AB + i * AS_ + j * 2) = (unsigned short)(pkbf(ab, 0.f) & 0xffffu);
;             }
;         }
	v_cmp_ge_i32_e64 s[46:47], 0, v222
	v_cmp_le_i32_e64 s[48:49], 0, v222
	v_mul_f32_e32 v40, 0x3db504f3, v2
	v_pk_mul_f32 v[42:43], v[136:137], v[40:41] op_sel_hi:[1,0]
	s_nop 0
	v_cndmask_b32_e64 v42, 0, v42, s[46:47]
	v_cndmask_b32_e64 v43, 0, v43, s[48:49]
	v_cvt_pk_bf16_f32 v42, v42, v43
	ds_write_b16 v228, v42
	ds_write_b16_d16_hi v229, v42
	v_cmp_ge_i32_e64 s[46:47], 1, v222
	v_cmp_le_i32_e64 s[48:49], 1, v222
	v_mul_f32_e32 v40, 0x3db504f3, v3
	v_pk_mul_f32 v[42:43], v[138:139], v[40:41] op_sel_hi:[1,0]
	s_nop 0
	v_cndmask_b32_e64 v42, 0, v42, s[46:47]
	v_cndmask_b32_e64 v43, 0, v43, s[48:49]
	v_cvt_pk_bf16_f32 v42, v42, v43
	ds_write_b16 v228, v42 offset:144
	ds_write_b16_d16_hi v229, v42 offset:144
	v_cmp_ge_i32_e64 s[46:47], 2, v222
	v_cmp_le_i32_e64 s[48:49], 2, v222
	v_mul_f32_e32 v40, 0x3db504f3, v4
	v_pk_mul_f32 v[42:43], v[140:141], v[40:41] op_sel_hi:[1,0]
	s_nop 0
	v_cndmask_b32_e64 v42, 0, v42, s[46:47]
	v_cndmask_b32_e64 v43, 0, v43, s[48:49]
	v_cvt_pk_bf16_f32 v42, v42, v43
	ds_write_b16 v228, v42 offset:288
	ds_write_b16_d16_hi v229, v42 offset:288
	v_cmp_ge_i32_e64 s[46:47], 3, v222
	v_cmp_le_i32_e64 s[48:49], 3, v222
	v_mul_f32_e32 v40, 0x3db504f3, v5
	v_pk_mul_f32 v[42:43], v[142:143], v[40:41] op_sel_hi:[1,0]
	s_nop 0
	v_cndmask_b32_e64 v42, 0, v42, s[46:47]
	v_cndmask_b32_e64 v43, 0, v43, s[48:49]
	v_cvt_pk_bf16_f32 v42, v42, v43
	ds_write_b16 v228, v42 offset:432
	ds_write_b16_d16_hi v229, v42 offset:432
	v_cmp_ge_i32_e64 s[46:47], 8, v222
	v_cmp_le_i32_e64 s[48:49], 8, v222
	v_mul_f32_e32 v40, 0x3db504f3, v6
	v_pk_mul_f32 v[42:43], v[144:145], v[40:41] op_sel_hi:[1,0]
	s_nop 0
	v_cndmask_b32_e64 v42, 0, v42, s[46:47]
	v_cndmask_b32_e64 v43, 0, v43, s[48:49]
	v_cvt_pk_bf16_f32 v42, v42, v43
	ds_write_b16 v228, v42 offset:1152
	ds_write_b16_d16_hi v229, v42 offset:1152
	v_cmp_ge_i32_e64 s[46:47], 9, v222
	v_cmp_le_i32_e64 s[48:49], 9, v222
	v_mul_f32_e32 v40, 0x3db504f3, v7
	v_pk_mul_f32 v[42:43], v[146:147], v[40:41] op_sel_hi:[1,0]
	s_nop 0
	v_cndmask_b32_e64 v42, 0, v42, s[46:47]
	v_cndmask_b32_e64 v43, 0, v43, s[48:49]
	v_cvt_pk_bf16_f32 v42, v42, v43
	ds_write_b16 v228, v42 offset:1296
	ds_write_b16_d16_hi v229, v42 offset:1296
	v_cmp_ge_i32_e64 s[46:47], 10, v222
	v_cmp_le_i32_e64 s[48:49], 10, v222
	v_mul_f32_e32 v40, 0x3db504f3, v8
	v_pk_mul_f32 v[42:43], v[148:149], v[40:41] op_sel_hi:[1,0]
	s_nop 0
	v_cndmask_b32_e64 v42, 0, v42, s[46:47]
	v_cndmask_b32_e64 v43, 0, v43, s[48:49]
	v_cvt_pk_bf16_f32 v42, v42, v43
	ds_write_b16 v228, v42 offset:1440
	ds_write_b16_d16_hi v229, v42 offset:1440
	v_cmp_ge_i32_e64 s[46:47], 11, v222
	v_cmp_le_i32_e64 s[48:49], 11, v222
	v_mul_f32_e32 v40, 0x3db504f3, v9
	v_pk_mul_f32 v[42:43], v[150:151], v[40:41] op_sel_hi:[1,0]
	s_nop 0
	v_cndmask_b32_e64 v42, 0, v42, s[46:47]
	v_cndmask_b32_e64 v43, 0, v43, s[48:49]
	v_cvt_pk_bf16_f32 v42, v42, v43
	ds_write_b16 v228, v42 offset:1584
	ds_write_b16_d16_hi v229, v42 offset:1584
	v_cmp_ge_i32_e64 s[46:47], 16, v222
	v_cmp_le_i32_e64 s[48:49], 16, v222
	v_mul_f32_e32 v40, 0x3db504f3, v10
	v_pk_mul_f32 v[42:43], v[152:153], v[40:41] op_sel_hi:[1,0]
	s_nop 0
	v_cndmask_b32_e64 v42, 0, v42, s[46:47]
	v_cndmask_b32_e64 v43, 0, v43, s[48:49]
	v_cvt_pk_bf16_f32 v42, v42, v43
	ds_write_b16 v228, v42 offset:2304
	ds_write_b16_d16_hi v229, v42 offset:2304
	v_cmp_ge_i32_e64 s[46:47], 17, v222
	v_cmp_le_i32_e64 s[48:49], 17, v222
	v_mul_f32_e32 v40, 0x3db504f3, v11
	v_pk_mul_f32 v[42:43], v[154:155], v[40:41] op_sel_hi:[1,0]
	s_nop 0
	v_cndmask_b32_e64 v42, 0, v42, s[46:47]
	v_cndmask_b32_e64 v43, 0, v43, s[48:49]
	v_cvt_pk_bf16_f32 v42, v42, v43
	ds_write_b16 v228, v42 offset:2448
	ds_write_b16_d16_hi v229, v42 offset:2448
	v_cmp_ge_i32_e64 s[46:47], 18, v222
	v_cmp_le_i32_e64 s[48:49], 18, v222
	v_mul_f32_e32 v40, 0x3db504f3, v12
	v_pk_mul_f32 v[42:43], v[156:157], v[40:41] op_sel_hi:[1,0]
	s_nop 0
	v_cndmask_b32_e64 v42, 0, v42, s[46:47]
	v_cndmask_b32_e64 v43, 0, v43, s[48:49]
	v_cvt_pk_bf16_f32 v42, v42, v43
	ds_write_b16 v228, v42 offset:2592
	ds_write_b16_d16_hi v229, v42 offset:2592
	v_cmp_ge_i32_e64 s[46:47], 19, v222
	v_cmp_le_i32_e64 s[48:49], 19, v222
	v_mul_f32_e32 v40, 0x3db504f3, v13
	v_pk_mul_f32 v[42:43], v[158:159], v[40:41] op_sel_hi:[1,0]
	s_nop 0
	v_cndmask_b32_e64 v42, 0, v42, s[46:47]
	v_cndmask_b32_e64 v43, 0, v43, s[48:49]
	v_cvt_pk_bf16_f32 v42, v42, v43
	ds_write_b16 v228, v42 offset:2736
	ds_write_b16_d16_hi v229, v42 offset:2736
	v_cmp_ge_i32_e64 s[46:47], 24, v222
	v_cmp_le_i32_e64 s[48:49], 24, v222
	v_mul_f32_e32 v40, 0x3db504f3, v14
	v_pk_mul_f32 v[42:43], v[160:161], v[40:41] op_sel_hi:[1,0]
	s_nop 0
	v_cndmask_b32_e64 v42, 0, v42, s[46:47]
	v_cndmask_b32_e64 v43, 0, v43, s[48:49]
	v_cvt_pk_bf16_f32 v42, v42, v43
	ds_write_b16 v228, v42 offset:3456
	ds_write_b16_d16_hi v229, v42 offset:3456
	v_cmp_ge_i32_e64 s[46:47], 25, v222
	v_cmp_le_i32_e64 s[48:49], 25, v222
	v_mul_f32_e32 v40, 0x3db504f3, v15
	v_pk_mul_f32 v[42:43], v[162:163], v[40:41] op_sel_hi:[1,0]
	s_nop 0
	v_cndmask_b32_e64 v42, 0, v42, s[46:47]
	v_cndmask_b32_e64 v43, 0, v43, s[48:49]
	v_cvt_pk_bf16_f32 v42, v42, v43
	ds_write_b16 v228, v42 offset:3600
	ds_write_b16_d16_hi v229, v42 offset:3600
	v_cmp_ge_i32_e64 s[46:47], 26, v222
	v_cmp_le_i32_e64 s[48:49], 26, v222
	v_mul_f32_e32 v40, 0x3db504f3, v16
	v_pk_mul_f32 v[42:43], v[230:231], v[40:41] op_sel_hi:[1,0]
	s_nop 0
	v_cndmask_b32_e64 v42, 0, v42, s[46:47]
	v_cndmask_b32_e64 v43, 0, v43, s[48:49]
	v_cvt_pk_bf16_f32 v42, v42, v43
	ds_write_b16 v228, v42 offset:3744
	ds_write_b16_d16_hi v229, v42 offset:3744
	v_cmp_ge_i32_e64 s[46:47], 27, v222
	v_cmp_le_i32_e64 s[48:49], 27, v222
	v_mul_f32_e32 v40, 0x3db504f3, v17
	v_pk_mul_f32 v[42:43], v[232:233], v[40:41] op_sel_hi:[1,0]
	s_nop 0
	v_cndmask_b32_e64 v42, 0, v42, s[46:47]
	v_cndmask_b32_e64 v43, 0, v43, s[48:49]
	v_cvt_pk_bf16_f32 v42, v42, v43
	ds_write_b16 v228, v42 offset:3888
	ds_write_b16_d16_hi v229, v42 offset:3888
	s_branch .Ls3_done
; #define LAS __attribute__((address_space(3)))
; __device__ __forceinline__ unsigned pkbf(float a, float b) { bf16x2_t v = __builtin_convertvector((f32x2_t){a, b}, bf16x2_t); return __builtin_bit_cast(unsigned, v); }
; __device__ __forceinline__ void gdn_prep_phase(LAS unsigned char* lds, const GdnPrepArgs& A, int bid, int G, const unsigned char* zero_page) {
;     ...
; #pragma unroll
;         for (int reg = 0; reg < 16; ++reg) {
;             const int i = 32 * rt + (reg & 3) + 8 * (reg >> 2) + 4 * hh; const float val = acc[reg];
;             const float ef = __expf(sc[i] - gfj), eb = __expf(sc[64 + i] - gbj);
;             if (which == 0) {
;                 const float lf = (i > j) ? sc[128 + i] * val * ef : 0.f, lb = (i < j) ? sc[192 + i] * val * eb : 0.f;
;                 ((LAS float*)(lds + L_LPF))[i * 64 + (j & 3) * 16 + (j >> 2)] = lf;
;                 const int i2 = 63 - i, j2 = 63 - j;
;                 ((LAS float*)(lds + L_LPB))[i2 * 64 + (j2 & 3) * 16 + (j2 >> 2)] = lb;
;             } else {
;                 const float af = (i >= j) ? QSCALE * val * ef : 0.f, ab = (i <= j) ? QSCALE * val * eb : 0.f;
;                 *(LAS unsigned short*)(lds + L_AF + i * AS_ + j * 2) = (unsigned short)(pkbf(af, 0.f) & 0xffffu);
;                 *(LAS unsigned short*)(lds + L_AB + i * AS_ + j * 2) = (unsigned short)(pkbf(ab, 0.f) & 0xffffu);
;             }
;         }
.Ls3_lpath:
	v_cmp_gt_i32_e64 s[46:47], 0, v222
	v_cmp_lt_i32_e64 s[48:49], 0, v222
	v_pk_mul_f32 v[234:235], v[234:235], v[2:3] op_sel_hi:[1,0]
	s_nop 0
	v_pk_mul_f32 v[234:235], v[234:235], v[136:137]
	s_nop 0
	v_cndmask_b32_e64 v234, 0, v234, s[46:47]
	v_cndmask_b32_e64 v235, 0, v235, s[48:49]
	ds_write_b32 v192, v234
	ds_write_b32 v73, v235
	v_cmp_gt_i32_e64 s[46:47], 1, v222
	v_cmp_lt_i32_e64 s[48:49], 1, v222
	v_pk_mul_f32 v[236:237], v[236:237], v[2:3] op_sel:[0,1] op_sel_hi:[1,1]
	s_nop 0
	v_pk_mul_f32 v[236:237], v[236:237], v[138:139]
	s_nop 0
	v_cndmask_b32_e64 v236, 0, v236, s[46:47]
	v_cndmask_b32_e64 v237, 0, v237, s[48:49]
	ds_write_b32 v193, v236
	ds_write_b32 v75, v237
	v_cmp_gt_i32_e64 s[46:47], 2, v222
	v_cmp_lt_i32_e64 s[48:49], 2, v222
	v_pk_mul_f32 v[238:239], v[238:239], v[4:5] op_sel_hi:[1,0]
	s_nop 0
	v_pk_mul_f32 v[238:239], v[238:239], v[140:141]
	s_nop 0
	v_cndmask_b32_e64 v238, 0, v238, s[46:47]
	v_cndmask_b32_e64 v239, 0, v239, s[48:49]
	ds_write_b32 v194, v238
	ds_write_b32 v77, v239
	v_cmp_gt_i32_e64 s[46:47], 3, v222
	v_cmp_lt_i32_e64 s[48:49], 3, v222
	v_pk_mul_f32 v[240:241], v[240:241], v[4:5] op_sel:[0,1] op_sel_hi:[1,1]
	s_nop 0
	v_pk_mul_f32 v[240:241], v[240:241], v[142:143]
	s_nop 0
	v_cndmask_b32_e64 v240, 0, v240, s[46:47]
	v_cndmask_b32_e64 v241, 0, v241, s[48:49]
	ds_write_b32 v195, v240
	ds_write_b32 v79, v241
	v_cmp_gt_i32_e64 s[46:47], 8, v222
	v_cmp_lt_i32_e64 s[48:49], 8, v222
	v_pk_mul_f32 v[242:243], v[242:243], v[6:7] op_sel_hi:[1,0]
	s_nop 0
	v_pk_mul_f32 v[242:243], v[242:243], v[144:145]
	s_nop 0
	v_cndmask_b32_e64 v242, 0, v242, s[46:47]
	v_cndmask_b32_e64 v243, 0, v243, s[48:49]
	ds_write_b32 v196, v242
	ds_write_b32 v81, v243
	v_cmp_gt_i32_e64 s[46:47], 9, v222
	v_cmp_lt_i32_e64 s[48:49], 9, v222
	v_pk_mul_f32 v[244:245], v[244:245], v[6:7] op_sel:[0,1] op_sel_hi:[1,1]
	s_nop 0
	v_pk_mul_f32 v[244:245], v[244:245], v[146:147]
	s_nop 0
	v_cndmask_b32_e64 v244, 0, v244, s[46:47]
	v_cndmask_b32_e64 v245, 0, v245, s[48:49]
	ds_write_b32 v197, v244
	ds_write_b32 v83, v245
	v_cmp_gt_i32_e64 s[46:47], 10, v222
	v_cmp_lt_i32_e64 s[48:49], 10, v222
	v_pk_mul_f32 v[248:249], v[248:249], v[8:9] op_sel_hi:[1,0]
	s_nop 0
	v_pk_mul_f32 v[248:249], v[248:249], v[148:149]
	s_nop 0
	v_cndmask_b32_e64 v248, 0, v248, s[46:47]
	v_cndmask_b32_e64 v249, 0, v249, s[48:49]
	ds_write_b32 v198, v248
	ds_write_b32 v85, v249
	v_cmp_gt_i32_e64 s[46:47], 11, v222
	v_cmp_lt_i32_e64 s[48:49], 11, v222
	v_pk_mul_f32 v[208:209], v[208:209], v[8:9] op_sel:[0,1] op_sel_hi:[1,1]
	s_nop 0
	v_pk_mul_f32 v[208:209], v[208:209], v[150:151]
	s_nop 0
	v_cndmask_b32_e64 v208, 0, v208, s[46:47]
	v_cndmask_b32_e64 v209, 0, v209, s[48:49]
	ds_write_b32 v199, v208
	ds_write_b32 v87, v209
	v_cmp_gt_i32_e64 s[46:47], 16, v222
	v_cmp_lt_i32_e64 s[48:49], 16, v222
	v_pk_mul_f32 v[210:211], v[210:211], v[10:11] op_sel_hi:[1,0]
	s_nop 0
	v_pk_mul_f32 v[210:211], v[210:211], v[152:153]
	s_nop 0
	v_cndmask_b32_e64 v210, 0, v210, s[46:47]
	v_cndmask_b32_e64 v211, 0, v211, s[48:49]
	ds_write_b32 v200, v210
	ds_write_b32 v89, v211
	v_cmp_gt_i32_e64 s[46:47], 17, v222
	v_cmp_lt_i32_e64 s[48:49], 17, v222
	v_pk_mul_f32 v[212:213], v[212:213], v[10:11] op_sel:[0,1] op_sel_hi:[1,1]
	s_nop 0
	v_pk_mul_f32 v[212:213], v[212:213], v[154:155]
	s_nop 0
	v_cndmask_b32_e64 v212, 0, v212, s[46:47]
	v_cndmask_b32_e64 v213, 0, v213, s[48:49]
	ds_write_b32 v201, v212
	ds_write_b32 v91, v213
	v_cmp_gt_i32_e64 s[46:47], 18, v222
	v_cmp_lt_i32_e64 s[48:49], 18, v222
	v_pk_mul_f32 v[214:215], v[214:215], v[12:13] op_sel_hi:[1,0]
	s_nop 0
	v_pk_mul_f32 v[214:215], v[214:215], v[156:157]
	s_nop 0
	v_cndmask_b32_e64 v214, 0, v214, s[46:47]
	v_cndmask_b32_e64 v215, 0, v215, s[48:49]
	ds_write_b32 v202, v214
	ds_write_b32 v93, v215
	v_cmp_gt_i32_e64 s[46:47], 19, v222
	v_cmp_lt_i32_e64 s[48:49], 19, v222
	v_pk_mul_f32 v[216:217], v[216:217], v[12:13] op_sel:[0,1] op_sel_hi:[1,1]
	s_nop 0
	v_pk_mul_f32 v[216:217], v[216:217], v[158:159]
	s_nop 0
	v_cndmask_b32_e64 v216, 0, v216, s[46:47]
	v_cndmask_b32_e64 v217, 0, v217, s[48:49]
	ds_write_b32 v203, v216
	ds_write_b32 v95, v217
	v_cmp_gt_i32_e64 s[46:47], 24, v222
	v_cmp_lt_i32_e64 s[48:49], 24, v222
	v_pk_mul_f32 v[218:219], v[218:219], v[14:15] op_sel_hi:[1,0]
	s_nop 0
	v_pk_mul_f32 v[218:219], v[218:219], v[160:161]
	s_nop 0
	v_cndmask_b32_e64 v218, 0, v218, s[46:47]
	v_cndmask_b32_e64 v219, 0, v219, s[48:49]
	ds_write_b32 v204, v218
	ds_write_b32 v97, v219
	v_cmp_gt_i32_e64 s[46:47], 25, v222
	v_cmp_lt_i32_e64 s[48:49], 25, v222
	v_pk_mul_f32 v[220:221], v[220:221], v[14:15] op_sel:[0,1] op_sel_hi:[1,1]
	s_nop 0
	v_pk_mul_f32 v[220:221], v[220:221], v[162:163]
	s_nop 0
	v_cndmask_b32_e64 v220, 0, v220, s[46:47]
	v_cndmask_b32_e64 v221, 0, v221, s[48:49]
	ds_write_b32 v205, v220
	ds_write_b32 v99, v221
	v_cmp_gt_i32_e64 s[46:47], 26, v222
	v_cmp_lt_i32_e64 s[48:49], 26, v222
	v_pk_mul_f32 v[46:47], v[46:47], v[16:17] op_sel_hi:[1,0]
	s_nop 0
	v_pk_mul_f32 v[46:47], v[46:47], v[230:231]
	s_nop 0
	v_cndmask_b32_e64 v46, 0, v46, s[46:47]
	v_cndmask_b32_e64 v47, 0, v47, s[48:49]
	ds_write_b32 v206, v46
	ds_write_b32 v101, v47
	v_cmp_gt_i32_e64 s[46:47], 27, v222
	v_cmp_lt_i32_e64 s[48:49], 27, v222
	v_pk_mul_f32 v[48:49], v[48:49], v[16:17] op_sel:[0,1] op_sel_hi:[1,1]
	s_nop 0
	v_pk_mul_f32 v[48:49], v[48:49], v[232:233]
	s_nop 0
	v_cndmask_b32_e64 v48, 0, v48, s[46:47]
	v_cndmask_b32_e64 v49, 0, v49, s[48:49]
	ds_write_b32 v207, v48
	ds_write_b32 v103, v49
; #define LAS __attribute__((address_space(3)))
; #define SOLVE_LD(i_) do { _Pragma("unroll") for (int a4 = 0; a4 < ((i_) + 15) / 16; ++a4) lq[(i_) % 3][a4] = *(const LAS f32x4*)(LP + (i_) * 64 + 4 * a4); } while (0)
; __device__ __forceinline__ void gdn_prep_phase(LAS unsigned char* lds, const GdnPrepArgs& A, int bid, int G, const unsigned char* zero_page) {
;     ...
;     if (!(pflg & 16)) {
;         const int dir = w >> 2, li = (w & 3) * 64 + lane, j = li >> 2, q = li & 3;
;         const LAS float* LP = (const LAS float*)(lds + (dir ? L_LPB : L_LPF)) + q * 16;
;         float t[16];
; #pragma unroll
;         for (int a = 0; a < 16; ++a) t[a] = 0.f;
;         f32x4 lq[3][4];
;     ...
;         SOLVE_LD(0); SOLVE_LD(1);
; #pragma unroll
;         for (int i = 0; i < 64; ++i) {
;             if (i + 2 < 48) SOLVE_LD(i + 2);
;             else if (i + 1 >= 48 && i + 1 < 64) SOLVE_LD(i + 1);
;             float p0 = 0.f, p1 = 0.f;
; #pragma unroll
;             for (int a4 = 0; a4 < (i + 15) / 16; ++a4) { const f32x4 lv = lq[i % 3][a4];
;                 p0 = __builtin_fmaf(lv.x, t[4 * a4], p0); p1 = __builtin_fmaf(lv.y, t[4 * a4 + 1], p1); p0 = __builtin_fmaf(lv.z, t[4 * a4 + 2], p0); p1 = __builtin_fmaf(lv.w, t[4 * a4 + 3], p1); }
;             float p = quad_sum(p0 + p1);
;             const float ti = (i == j ? 1.f : 0.f) - p;
;             if (q == (i & 3)) t[i >> 2] = ti;
.Ls3_done:
	s_waitcnt lgkmcnt(0)
	s_barrier
	ds_read_b128 v[32:35], v173 offset:256
	ds_read_b128 v[36:39], v173 offset:512
	ds_read_b128 v[40:43], v173 offset:768
	ds_read_b128 v[44:47], v173 offset:1024
	ds_read_b128 v[6:9], v173 offset:1280
	ds_read_b128 v[10:13], v173 offset:1536
	ds_read_b128 v[14:17], v173 offset:1792
	ds_read_b128 v[238:241], v173 offset:2048
	ds_read_b128 v[136:139], v173 offset:2304
	ds_read_b128 v[140:143], v173 offset:2560
	ds_read_b128 v[144:147], v173 offset:2816
	ds_read_b128 v[148:151], v173 offset:3072
	ds_read_b128 v[152:155], v173 offset:3328
	ds_read_b128 v[156:159], v173 offset:3584
	ds_read_b128 v[160:163], v173 offset:3840
	v_mov_b32_e32 v233, 0
	v_mov_b32_e32 v234, 0
	v_mov_b32_e32 v235, 0
	v_cndmask_b32_e64 v232, 0, v104, s[86:87]
	s_waitcnt lgkmcnt(14)
	v_pk_fma_f32 v[32:33], v[32:33], v[232:233], 0 op_sel_hi:[1,1,0]
	s_nop 0
	v_add_f32_e32 v32, v32, v33
	s_nop 1
	v_add_f32_dpp v32, v32, v32 quad_perm:[1,0,3,2] row_mask:0xf bank_mask:0xf bound_ctrl:1
	s_nop 1
	v_add_f32_dpp v32, v32, v32 quad_perm:[2,3,0,1] row_mask:0xf bank_mask:0xf bound_ctrl:1
	v_sub_f32_e32 v32, v105, v32
	v_cndmask_b32_e64 v232, v232, v32, s[88:89]
	s_waitcnt lgkmcnt(13)
	v_pk_fma_f32 v[36:37], v[36:37], v[232:233], 0 op_sel_hi:[1,1,0]
	s_nop 0
	v_add_f32_e32 v36, v36, v37
	s_nop 1
	v_add_f32_dpp v36, v36, v36 quad_perm:[1,0,3,2] row_mask:0xf bank_mask:0xf bound_ctrl:1
	s_nop 1
	v_add_f32_dpp v36, v36, v36 quad_perm:[2,3,0,1] row_mask:0xf bank_mask:0xf bound_ctrl:1
	v_sub_f32_e32 v36, v106, v36
	v_cndmask_b32_e64 v232, v232, v36, s[90:91]
	s_waitcnt lgkmcnt(12)
	v_pk_fma_f32 v[40:41], v[40:41], v[232:233], 0 op_sel_hi:[1,1,0]
	s_nop 0
	v_add_f32_e32 v40, v40, v41
	s_nop 1
	v_add_f32_dpp v40, v40, v40 quad_perm:[1,0,3,2] row_mask:0xf bank_mask:0xf bound_ctrl:1
	s_nop 1
	v_add_f32_dpp v40, v40, v40 quad_perm:[2,3,0,1] row_mask:0xf bank_mask:0xf bound_ctrl:1
	v_sub_f32_e32 v40, v107, v40
	v_cndmask_b32_e64 v232, v232, v40, s[92:93]
	s_waitcnt lgkmcnt(11)
	v_pk_fma_f32 v[44:45], v[44:45], v[232:233], 0 op_sel_hi:[1,1,0]
	s_nop 0
	v_add_f32_e32 v44, v44, v45
	s_nop 1
	v_add_f32_dpp v44, v44, v44 quad_perm:[1,0,3,2] row_mask:0xf bank_mask:0xf bound_ctrl:1
	s_nop 1
	v_add_f32_dpp v44, v44, v44 quad_perm:[2,3,0,1] row_mask:0xf bank_mask:0xf bound_ctrl:1
	v_sub_f32_e32 v44, v109, v44
	v_cndmask_b32_e64 v233, v233, v44, s[86:87]
	s_waitcnt lgkmcnt(10)
	v_pk_fma_f32 v[6:7], v[6:7], v[232:233], 0 op_sel_hi:[1,1,0]
	s_nop 0
	v_add_f32_e32 v6, v6, v7
	s_nop 1
	v_add_f32_dpp v6, v6, v6 quad_perm:[1,0,3,2] row_mask:0xf bank_mask:0xf bound_ctrl:1
	s_nop 1
	v_add_f32_dpp v6, v6, v6 quad_perm:[2,3,0,1] row_mask:0xf bank_mask:0xf bound_ctrl:1
	v_sub_f32_e32 v6, v110, v6
	v_cndmask_b32_e64 v233, v233, v6, s[88:89]
	s_waitcnt lgkmcnt(9)
	v_pk_fma_f32 v[10:11], v[10:11], v[232:233], 0 op_sel_hi:[1,1,0]
	s_nop 0
	v_add_f32_e32 v10, v10, v11
	s_nop 1
	v_add_f32_dpp v10, v10, v10 quad_perm:[1,0,3,2] row_mask:0xf bank_mask:0xf bound_ctrl:1
	s_nop 1
	v_add_f32_dpp v10, v10, v10 quad_perm:[2,3,0,1] row_mask:0xf bank_mask:0xf bound_ctrl:1
	v_sub_f32_e32 v10, v111, v10
	v_cndmask_b32_e64 v233, v233, v10, s[90:91]
	s_waitcnt lgkmcnt(8)
	v_pk_fma_f32 v[14:15], v[14:15], v[232:233], 0 op_sel_hi:[1,1,0]
	s_nop 0
	v_add_f32_e32 v14, v14, v15
	s_nop 1
	v_add_f32_dpp v14, v14, v14 quad_perm:[1,0,3,2] row_mask:0xf bank_mask:0xf bound_ctrl:1
	s_nop 1
	v_add_f32_dpp v14, v14, v14 quad_perm:[2,3,0,1] row_mask:0xf bank_mask:0xf bound_ctrl:1
	v_sub_f32_e32 v14, v112, v14
	v_cndmask_b32_e64 v233, v233, v14, s[92:93]
	s_waitcnt lgkmcnt(7)
	v_pk_fma_f32 v[238:239], v[238:239], v[232:233], 0 op_sel_hi:[1,1,0]
	s_nop 0
	v_add_f32_e32 v238, v238, v239
	s_nop 1
	v_add_f32_dpp v238, v238, v238 quad_perm:[1,0,3,2] row_mask:0xf bank_mask:0xf bound_ctrl:1
	s_nop 1
	v_add_f32_dpp v238, v238, v238 quad_perm:[2,3,0,1] row_mask:0xf bank_mask:0xf bound_ctrl:1
	v_sub_f32_e32 v238, v113, v238
	v_cndmask_b32_e64 v234, v234, v238, s[86:87]
	s_waitcnt lgkmcnt(6)
	v_pk_fma_f32 v[136:137], v[136:137], v[232:233], 0 op_sel_hi:[1,1,0]
	s_nop 0
	v_pk_fma_f32 v[136:137], v[138:139], v[234:235], v[136:137]
	s_nop 0
	v_add_f32_e32 v136, v136, v137
	s_nop 1
	v_add_f32_dpp v136, v136, v136 quad_perm:[1,0,3,2] row_mask:0xf bank_mask:0xf bound_ctrl:1
	s_nop 1
	v_add_f32_dpp v136, v136, v136 quad_perm:[2,3,0,1] row_mask:0xf bank_mask:0xf bound_ctrl:1
	v_sub_f32_e32 v136, v114, v136
	v_cndmask_b32_e64 v234, v234, v136, s[88:89]
	s_waitcnt lgkmcnt(5)
	v_pk_fma_f32 v[140:141], v[140:141], v[232:233], 0 op_sel_hi:[1,1,0]
	s_nop 0
	v_pk_fma_f32 v[140:141], v[142:143], v[234:235], v[140:141]
	s_nop 0
	v_add_f32_e32 v140, v140, v141
	s_nop 1
	v_add_f32_dpp v140, v140, v140 quad_perm:[1,0,3,2] row_mask:0xf bank_mask:0xf bound_ctrl:1
	s_nop 1
	v_add_f32_dpp v140, v140, v140 quad_perm:[2,3,0,1] row_mask:0xf bank_mask:0xf bound_ctrl:1
	v_sub_f32_e32 v140, v115, v140
	v_cndmask_b32_e64 v234, v234, v140, s[90:91]
	s_waitcnt lgkmcnt(4)
	v_pk_fma_f32 v[144:145], v[144:145], v[232:233], 0 op_sel_hi:[1,1,0]
	s_nop 0
	v_pk_fma_f32 v[144:145], v[146:147], v[234:235], v[144:145]
	s_nop 0
	v_add_f32_e32 v144, v144, v145
	s_nop 1
	v_add_f32_dpp v144, v144, v144 quad_perm:[1,0,3,2] row_mask:0xf bank_mask:0xf bound_ctrl:1
	s_nop 1
	v_add_f32_dpp v144, v144, v144 quad_perm:[2,3,0,1] row_mask:0xf bank_mask:0xf bound_ctrl:1
	v_sub_f32_e32 v144, v116, v144
	v_cndmask_b32_e64 v234, v234, v144, s[92:93]
	s_waitcnt lgkmcnt(3)
; #define LAS __attribute__((address_space(3)))
; #define SOLVE_LD(i_) do { _Pragma("unroll") for (int a4 = 0; a4 < ((i_) + 15) / 16; ++a4) lq[(i_) % 3][a4] = *(const LAS f32x4*)(LP + (i_) * 64 + 4 * a4); } while (0)
; __device__ __forceinline__ void gdn_prep_phase(LAS unsigned char* lds, const GdnPrepArgs& A, int bid, int G, const unsigned char* zero_page) {
;     ...
;     if (!(pflg & 16)) {
;         const int dir = w >> 2, li = (w & 3) * 64 + lane, j = li >> 2, q = li & 3;
;         const LAS float* LP = (const LAS float*)(lds + (dir ? L_LPB : L_LPF)) + q * 16;
;         float t[16];
; #pragma unroll
;         for (int a = 0; a < 16; ++a) t[a] = 0.f;
;         f32x4 lq[3][4];
;     ...
;         SOLVE_LD(0); SOLVE_LD(1);
; #pragma unroll
;         for (int i = 0; i < 64; ++i) {
;             if (i + 2 < 48) SOLVE_LD(i + 2);
;             else if (i + 1 >= 48 && i + 1 < 64) SOLVE_LD(i + 1);
;             float p0 = 0.f, p1 = 0.f;
; #pragma unroll
;             for (int a4 = 0; a4 < (i + 15) / 16; ++a4) { const f32x4 lv = lq[i % 3][a4];
;                 p0 = __builtin_fmaf(lv.x, t[4 * a4], p0); p1 = __builtin_fmaf(lv.y, t[4 * a4 + 1], p1); p0 = __builtin_fmaf(lv.z, t[4 * a4 + 2], p0); p1 = __builtin_fmaf(lv.w, t[4 * a4 + 3], p1); }
;             float p = quad_sum(p0 + p1);
;             const float ti = (i == j ? 1.f : 0.f) - p;
;             if (q == (i & 3)) t[i >> 2] = ti;
;             if ((i & 7) == 3 && !(pflg & 64)) {
;                 constexpr int kk = 0; const int k8 = i >> 3, b = w + 8 * (k8 & 1); v4u f; int off; (void)kk;
;                 if (k8 < 2)      { f = frag16_rm(lds + L_KN, QS_, b >> 2, b & 3, lane); off = B_KA + b * 1024; }
;                 else if (k8 < 4) { f = frag16_rm(lds + L_QN, QS_, b >> 2, b & 3, lane); off = B_QA + b * 1024; }
;                 else if (k8 < 6) { f = frag16_tr(lds + L_KN, QS_, b >> 1, b & 1, lane); off = B_KT + b * 1024; }
;                 else             { f = frag16_rm(lds + (k8 == 6 ? L_AF : L_AB), AS_, w >> 1, w & 1, lane); off = (k8 == 6 ? B_AF : B_AB) + w * 1024; }
;                 *(v4u*)(blob + off + lane * 16) = f; }
;             __builtin_amdgcn_sched_barrier(0);
;         }
	v_pk_fma_f32 v[148:149], v[148:149], v[232:233], 0 op_sel_hi:[1,1,0]
	s_nop 0
	v_pk_fma_f32 v[148:149], v[150:151], v[234:235], v[148:149]
	s_nop 0
	v_add_f32_e32 v148, v148, v149
	s_nop 1
	v_add_f32_dpp v148, v148, v148 quad_perm:[1,0,3,2] row_mask:0xf bank_mask:0xf bound_ctrl:1
	s_nop 1
	v_add_f32_dpp v148, v148, v148 quad_perm:[2,3,0,1] row_mask:0xf bank_mask:0xf bound_ctrl:1
	v_sub_f32_e32 v148, v118, v148
	v_cndmask_b32_e64 v235, v235, v148, s[86:87]
	s_waitcnt lgkmcnt(2)
	v_pk_fma_f32 v[152:153], v[152:153], v[232:233], 0 op_sel_hi:[1,1,0]
	s_nop 0
	v_pk_fma_f32 v[152:153], v[154:155], v[234:235], v[152:153]
	s_nop 0
	v_add_f32_e32 v152, v152, v153
	s_nop 1
	v_add_f32_dpp v152, v152, v152 quad_perm:[1,0,3,2] row_mask:0xf bank_mask:0xf bound_ctrl:1
	s_nop 1
	v_add_f32_dpp v152, v152, v152 quad_perm:[2,3,0,1] row_mask:0xf bank_mask:0xf bound_ctrl:1
	v_sub_f32_e32 v152, v119, v152
	v_cndmask_b32_e64 v235, v235, v152, s[88:89]
	s_waitcnt lgkmcnt(1)
	v_pk_fma_f32 v[156:157], v[156:157], v[232:233], 0 op_sel_hi:[1,1,0]
	s_nop 0
	v_pk_fma_f32 v[156:157], v[158:159], v[234:235], v[156:157]
	s_nop 0
	v_add_f32_e32 v156, v156, v157
	s_nop 1
	v_add_f32_dpp v156, v156, v156 quad_perm:[1,0,3,2] row_mask:0xf bank_mask:0xf bound_ctrl:1
	s_nop 1
	v_add_f32_dpp v156, v156, v156 quad_perm:[2,3,0,1] row_mask:0xf bank_mask:0xf bound_ctrl:1
	v_sub_f32_e32 v156, v120, v156
	v_cndmask_b32_e64 v235, v235, v156, s[90:91]
	s_waitcnt lgkmcnt(0)
	v_pk_fma_f32 v[160:161], v[160:161], v[232:233], 0 op_sel_hi:[1,1,0]
	s_nop 0
	v_pk_fma_f32 v[160:161], v[162:163], v[234:235], v[160:161]
	s_nop 0
	v_add_f32_e32 v160, v160, v161
	s_nop 1
	v_add_f32_dpp v160, v160, v160 quad_perm:[1,0,3,2] row_mask:0xf bank_mask:0xf bound_ctrl:1
	s_nop 1
	v_add_f32_dpp v160, v160, v160 quad_perm:[2,3,0,1] row_mask:0xf bank_mask:0xf bound_ctrl:1
	v_sub_f32_e32 v160, v121, v160
	v_cndmask_b32_e64 v235, v235, v160, s[92:93]
	ds_write_b32 v174, v232
	ds_write_b32 v174, v233 offset:16
	ds_write_b32 v174, v234 offset:32
	ds_write_b32 v174, v235 offset:48
	v_xor_b32_e32 v6, 0x80000000, v232
	v_xor_b32_e32 v7, 0x80000000, v233
	v_xor_b32_e32 v8, 0x80000000, v234
	v_xor_b32_e32 v9, 0x80000000, v235
	ds_write_b32 v175, v6
	ds_write_b32 v175, v7 offset:256
	ds_write_b32 v175, v8 offset:512
	ds_write_b32 v175, v9 offset:768
	s_waitcnt lgkmcnt(0)
	s_barrier
	ds_read_b128 v[136:139], v180
	s_cmp_gt_u32 s101, 2
	s_cbranch_scc1 .Ls4b_end
	ds_read2_b32 v[144:145], v176 offset0:0 offset1:16
	ds_read2_b32 v[146:147], v176 offset0:32 offset1:48
	ds_read_b128 v[140:143], v179 offset:2048
	s_waitcnt lgkmcnt(2)
	v_mfma_f32_16x16x4_f32 v[156:159], v144, v136, 0
	v_mfma_f32_16x16x4_f32 v[156:159], v145, v137, v[156:159]
	s_waitcnt lgkmcnt(1)
	v_mfma_f32_16x16x4_f32 v[156:159], v146, v138, v[156:159]
	v_mfma_f32_16x16x4_f32 v[156:159], v147, v139, v[156:159]
	s_waitcnt lgkmcnt(0)
	s_nop 8
	v_mfma_f32_16x16x4_f32 v[160:163], v140, v156, 0
	v_mfma_f32_16x16x4_f32 v[160:163], v141, v157, v[160:163]
	v_mfma_f32_16x16x4_f32 v[160:163], v142, v158, v[160:163]
	v_mfma_f32_16x16x4_f32 v[160:163], v143, v159, v[160:163]
	s_cmp_gt_u32 s101, 1
	s_cbranch_scc1 .Ls4b_end
	ds_read2_b32 v[144:145], v177 offset0:0 offset1:16
	ds_read2_b32 v[146:147], v177 offset0:32 offset1:48
	ds_read2_b32 v[148:149], v177 offset0:4 offset1:20
	ds_read2_b32 v[150:151], v177 offset0:36 offset1:52
	ds_read_b128 v[140:143], v179 offset:4096
	s_waitcnt lgkmcnt(4)
	v_mfma_f32_16x16x4_f32 v[156:159], v144, v136, 0
	v_mfma_f32_16x16x4_f32 v[156:159], v145, v137, v[156:159]
	s_waitcnt lgkmcnt(3)
	v_mfma_f32_16x16x4_f32 v[156:159], v146, v138, v[156:159]
	v_mfma_f32_16x16x4_f32 v[156:159], v147, v139, v[156:159]
	s_waitcnt lgkmcnt(2)
	v_mfma_f32_16x16x4_f32 v[156:159], v148, v160, v[156:159]
	v_mfma_f32_16x16x4_f32 v[156:159], v149, v161, v[156:159]
	s_waitcnt lgkmcnt(1)
	v_mfma_f32_16x16x4_f32 v[156:159], v150, v162, v[156:159]
	v_mfma_f32_16x16x4_f32 v[156:159], v151, v163, v[156:159]
	s_waitcnt lgkmcnt(0)
	s_nop 8
	v_mfma_f32_16x16x4_f32 v[122:125], v140, v156, 0
	v_mfma_f32_16x16x4_f32 v[122:125], v141, v157, v[122:125]
	v_mfma_f32_16x16x4_f32 v[122:125], v142, v158, v[122:125]
	v_mfma_f32_16x16x4_f32 v[122:125], v143, v159, v[122:125]
	s_cmp_gt_u32 s101, 0
	s_cbranch_scc1 .Ls4b_end
	ds_read2_b32 v[144:145], v178 offset0:0 offset1:16
	ds_read2_b32 v[146:147], v178 offset0:32 offset1:48
	ds_read2_b32 v[148:149], v178 offset0:4 offset1:20
	ds_read2_b32 v[150:151], v178 offset0:36 offset1:52
	ds_read2_b32 v[152:153], v178 offset0:8 offset1:24
	ds_read2_b32 v[154:155], v178 offset0:40 offset1:56
	ds_read_b128 v[140:143], v179 offset:6144
	s_waitcnt lgkmcnt(6)
	v_mfma_f32_16x16x4_f32 v[156:159], v144, v136, 0
	v_mfma_f32_16x16x4_f32 v[156:159], v145, v137, v[156:159]
	s_waitcnt lgkmcnt(5)
	v_mfma_f32_16x16x4_f32 v[156:159], v146, v138, v[156:159]
	v_mfma_f32_16x16x4_f32 v[156:159], v147, v139, v[156:159]
	s_waitcnt lgkmcnt(4)
	v_mfma_f32_16x16x4_f32 v[156:159], v148, v160, v[156:159]
	v_mfma_f32_16x16x4_f32 v[156:159], v149, v161, v[156:159]
	s_waitcnt lgkmcnt(3)
	v_mfma_f32_16x16x4_f32 v[156:159], v150, v162, v[156:159]
	v_mfma_f32_16x16x4_f32 v[156:159], v151, v163, v[156:159]
	s_waitcnt lgkmcnt(2)
	v_mfma_f32_16x16x4_f32 v[156:159], v152, v122, v[156:159]
	v_mfma_f32_16x16x4_f32 v[156:159], v153, v123, v[156:159]
	s_waitcnt lgkmcnt(1)
	v_mfma_f32_16x16x4_f32 v[156:159], v154, v124, v[156:159]
	v_mfma_f32_16x16x4_f32 v[156:159], v155, v125, v[156:159]
	s_waitcnt lgkmcnt(0)
	s_nop 8
	v_mfma_f32_16x16x4_f32 v[126:129], v140, v156, 0
	v_mfma_f32_16x16x4_f32 v[126:129], v141, v157, v[126:129]
	v_mfma_f32_16x16x4_f32 v[126:129], v142, v158, v[126:129]
	v_mfma_f32_16x16x4_f32 v[126:129], v143, v159, v[126:129]
; #define LAS __attribute__((address_space(3)))
; __device__ __forceinline__ unsigned pkbf(float a, float b) { bf16x2_t v = __builtin_convertvector((f32x2_t){a, b}, bf16x2_t); return __builtin_bit_cast(unsigned, v); }
; __device__ __forceinline__ void gdn_prep_phase(LAS unsigned char* lds, const GdnPrepArgs& A, int bid, int G, const unsigned char* zero_page) {
;     ...
;             if ((i & 7) == 3 && !(pflg & 64)) {
;                 constexpr int kk = 0; const int k8 = i >> 3, b = w + 8 * (k8 & 1); v4u f; int off; (void)kk;
;                 if (k8 < 2)      { f = frag16_rm(lds + L_KN, QS_, b >> 2, b & 3, lane); off = B_KA + b * 1024; }
;                 else if (k8 < 4) { f = frag16_rm(lds + L_QN, QS_, b >> 2, b & 3, lane); off = B_QA + b * 1024; }
;                 else if (k8 < 6) { f = frag16_tr(lds + L_KN, QS_, b >> 1, b & 1, lane); off = B_KT + b * 1024; }
;                 else             { f = frag16_rm(lds + (k8 == 6 ? L_AF : L_AB), AS_, w >> 1, w & 1, lane); off = (k8 == 6 ? B_AF : B_AB) + w * 1024; }
;                 *(v4u*)(blob + off + lane * 16) = f; }
;             __builtin_amdgcn_sched_barrier(0);
;         }
;     ...
;         const LAS float* sc = (const LAS float*)(lds + L_SC);
;         if (dir == 0) { const float bj = sc[128 + j];
; #pragma unroll
;             for (int a = 0; a < 16; ++a) *(LAS unsigned short*)(lds + L_TBF + (4 * a + q) * AS_ + j * 2) = (unsigned short)(pkbf(t[a] * bj, 0.f) & 0xffffu);
;         } else { const int jo = 63 - j; const float bj = sc[192 + jo];
; #pragma unroll
;             for (int a = 0; a < 16; ++a) *(LAS unsigned short*)(lds + L_TBB + (63 - (4 * a + q)) * AS_ + jo * 2) = (unsigned short)(pkbf(t[a] * bj, 0.f) & 0xffffu);
;         }
.Ls4b_end:
	s_waitcnt lgkmcnt(0)
	v_lshl_add_u64 v[6:7], s[40:41], 0, v[22:23]
	v_readlane_b32 s2, v255, 48
	v_add_u32_e32 v9, v63, v108
	ds_read2_b64 v[10:13], v9 offset1:4
	v_readlane_b32 s3, v255, 49
	s_nop 1
	v_lshl_add_u64 v[8:9], v[6:7], 0, s[2:3]
	s_waitcnt lgkmcnt(0)
	global_store_dwordx4 v[8:9], v[10:13], off
	v_add_u32_e32 v14, v63, v117
	ds_read2_b64 v[14:17], v14 offset1:4
	v_lshl_add_u64 v[32:33], v[6:7], 0, s[38:39]
	s_waitcnt lgkmcnt(0)
	global_store_dwordx4 v[32:33], v[14:17], off
	s_movk_i32 s40, 0x4000
	v_add_co_u32_e32 v12, vcc, s40, v8
	s_nop 1
	v_addc_co_u32_e32 v13, vcc, 0, v9, vcc
	v_add_u32_e32 v11, v62, v108
	v_add_u32_e32 v11, 0xc800, v11
	ds_read2_b64 v[34:37], v11 offset0:128 offset1:132
	s_waitcnt lgkmcnt(0)
	global_store_dwordx4 v[12:13], v[34:37], off
	v_add_co_u32_e32 v230, vcc, s40, v32
	s_nop 1
	v_addc_co_u32_e32 v231, vcc, 0, v33, vcc
	v_add_u32_e32 v13, v62, v117
	v_add_u32_e32 v13, 0xc800, v13
	ds_read2_b64 v[42:45], v13 offset0:128 offset1:132
	s_waitcnt lgkmcnt(0)
	global_store_dwordx4 v[230:231], v[42:45], off
	s_mov_b32 s40, 0x8000
	v_add_u32_e32 v15, s71, v61
	ds_read_u16 v16, v15 offset:816
	ds_read_u16 v17, v15 offset:4352
	ds_read_u16 v239, v15 offset:4624
	ds_read_u16 v240, v15 offset:4896
	ds_read_u16 v241, v15 offset:5168
	ds_read_u16 v242, v15
	ds_read_u16 v243, v15 offset:272
	ds_read_u16 v15, v15 offset:544
	s_waitcnt lgkmcnt(3)
	v_perm_b32 v241, v241, v240, s33
	v_perm_b32 v240, v239, v17, s33
	s_waitcnt lgkmcnt(0)
	v_perm_b32 v239, v16, v15, s33
	v_add_co_u32_e32 v16, vcc, s40, v8
	v_perm_b32 v238, v243, v242, s33
	s_nop 0
	v_addc_co_u32_e32 v17, vcc, 0, v9, vcc
	global_store_dwordx4 v[16:17], v[238:241], off offset:2048
	v_add_u32_e32 v38, s72, v61
	v_add_co_u32_e32 v32, vcc, s40, v32
	s_nop 1
	v_addc_co_u32_e32 v33, vcc, 0, v33, vcc
	ds_read_u16 v39, v38 offset:816
	ds_read_u16 v40, v38 offset:4352
	ds_read_u16 v46, v38 offset:4624
	ds_read_u16 v41, v38 offset:4896
	ds_read_u16 v47, v38 offset:5168
	ds_read_u16 v48, v38
	ds_read_u16 v49, v38 offset:272
	ds_read_u16 v38, v38 offset:544
	s_waitcnt lgkmcnt(3)
	v_perm_b32 v41, v47, v41, s33
	v_perm_b32 v40, v46, v40, s33
	s_waitcnt lgkmcnt(0)
	v_perm_b32 v39, v39, v38, s33
	v_perm_b32 v38, v49, v48, s33
	global_store_dwordx4 v[32:33], v[38:41], off offset:2048
	s_mov_b32 s40, 0xe000
	v_add_co_u32_e32 v46, vcc, s40, v8
	s_nop 1
	v_addc_co_u32_e32 v47, vcc, 0, v9, vcc
	ds_read_b64 v[42:43], v185
	ds_read_b64 v[44:45], v186
	s_waitcnt lgkmcnt(0)
	global_store_dwordx4 v[46:47], v[42:45], off offset:2048
	s_mov_b32 s40, 0x12000
	v_add_co_u32_e32 v8, vcc, s40, v8
	s_nop 1
	v_addc_co_u32_e32 v9, vcc, 0, v9, vcc
	ds_read_b64 v[40:41], v187
	ds_read_b64 v[42:43], v188
	s_waitcnt lgkmcnt(0)
	global_store_dwordx4 v[8:9], v[40:43], off offset:2048
	s_waitcnt lgkmcnt(0)
	s_barrier
	v_mov_b32_e32 v249, v181
	v_mov_b32_e32 v130, v183
	s_nop 0
	ds_read_b32 v236, v224
	ds_read_b32 v237, v246
	v_mov_b32_e32 v2, 0
	s_cmp_eq_u32 s101, 3
	s_cbranch_scc1 .Ls4o3
	s_cmp_eq_u32 s101, 2
	s_cbranch_scc1 .Ls4o2
	s_cmp_eq_u32 s101, 1
	s_cbranch_scc1 .Ls4o1
	s_waitcnt lgkmcnt(1)
	v_mul_f32_e32 v3, v232, v236
	v_cvt_pk_bf16_f32 v3, v3, s0
	ds_write_b16 v249, v3
	v_add_u32_e32 v249, v182, v249
	v_mul_f32_e32 v3, v233, v236
	v_cvt_pk_bf16_f32 v3, v3, s0
	ds_write_b16 v249, v3
	v_add_u32_e32 v249, v182, v249
	v_mul_f32_e32 v3, v234, v236
	v_cvt_pk_bf16_f32 v3, v3, s0
	ds_write_b16 v249, v3
	v_add_u32_e32 v249, v182, v249
	v_mul_f32_e32 v3, v235, v236
	v_cvt_pk_bf16_f32 v3, v3, s0
	ds_write_b16 v249, v3
	v_lshl_add_u32 v130, v184, 4, v130
	v_mov_b32_e32 v4, v130
	s_waitcnt lgkmcnt(4)
	v_mul_f32_e32 v3, v160, v237
	v_cvt_pk_bf16_f32 v3, v3, s0
	ds_write_b16 v4, v3
	v_add_u32_e32 v4, v184, v4
	v_mul_f32_e32 v3, v161, v237
	v_cvt_pk_bf16_f32 v3, v3, s0
	ds_write_b16 v4, v3
	v_add_u32_e32 v4, v184, v4
	v_mul_f32_e32 v3, v162, v237
	v_cvt_pk_bf16_f32 v3, v3, s0
	ds_write_b16 v4, v3
	v_add_u32_e32 v4, v184, v4
	v_mul_f32_e32 v3, v163, v237
	v_cvt_pk_bf16_f32 v3, v3, s0
	ds_write_b16 v4, v3
	v_lshl_add_u32 v130, v184, 4, v130
	v_mov_b32_e32 v4, v130
	v_mul_f32_e32 v3, v122, v237
	v_cvt_pk_bf16_f32 v3, v3, s0
	ds_write_b16 v4, v3
	v_add_u32_e32 v4, v184, v4
	v_mul_f32_e32 v3, v123, v237
	v_cvt_pk_bf16_f32 v3, v3, s0
	ds_write_b16 v4, v3
	v_add_u32_e32 v4, v184, v4
	v_mul_f32_e32 v3, v124, v237
	v_cvt_pk_bf16_f32 v3, v3, s0
	ds_write_b16 v4, v3
	v_add_u32_e32 v4, v184, v4
	v_mul_f32_e32 v3, v125, v237
	v_cvt_pk_bf16_f32 v3, v3, s0
	ds_write_b16 v4, v3
	v_lshl_add_u32 v130, v184, 4, v130
	v_mov_b32_e32 v4, v130
	v_mul_f32_e32 v3, v126, v237
	v_cvt_pk_bf16_f32 v3, v3, s0
	ds_write_b16 v4, v3
	v_add_u32_e32 v4, v184, v4
	v_mul_f32_e32 v3, v127, v237
	v_cvt_pk_bf16_f32 v3, v3, s0
	ds_write_b16 v4, v3
	v_add_u32_e32 v4, v184, v4
	v_mul_f32_e32 v3, v128, v237
	v_cvt_pk_bf16_f32 v3, v3, s0
	ds_write_b16 v4, v3
	v_add_u32_e32 v4, v184, v4
	v_mul_f32_e32 v3, v129, v237
	v_cvt_pk_bf16_f32 v3, v3, s0
	ds_write_b16 v4, v3
	s_branch .Ls4o_end
; #define LAS __attribute__((address_space(3)))
; __device__ __forceinline__ unsigned pkbf(float a, float b) { bf16x2_t v = __builtin_convertvector((f32x2_t){a, b}, bf16x2_t); return __builtin_bit_cast(unsigned, v); }
; __device__ __forceinline__ void gdn_prep_phase(LAS unsigned char* lds, const GdnPrepArgs& A, int bid, int G, const unsigned char* zero_page) {
;     ...
;         const LAS float* sc = (const LAS float*)(lds + L_SC);
;         if (dir == 0) { const float bj = sc[128 + j];
; #pragma unroll
;             for (int a = 0; a < 16; ++a) *(LAS unsigned short*)(lds + L_TBF + (4 * a + q) * AS_ + j * 2) = (unsigned short)(pkbf(t[a] * bj, 0.f) & 0xffffu);
;         } else { const int jo = 63 - j; const float bj = sc[192 + jo];
; #pragma unroll
;             for (int a = 0; a < 16; ++a) *(LAS unsigned short*)(lds + L_TBB + (63 - (4 * a + q)) * AS_ + jo * 2) = (unsigned short)(pkbf(t[a] * bj, 0.f) & 0xffffu);
;         }
.Ls4o1:
	s_waitcnt lgkmcnt(0)
	ds_write_b16 v249, v2
	v_add_u32_e32 v249, v182, v249
	ds_write_b16 v249, v2
	v_add_u32_e32 v249, v182, v249
	ds_write_b16 v249, v2
	v_add_u32_e32 v249, v182, v249
	ds_write_b16 v249, v2
	v_add_u32_e32 v249, v182, v249
	v_mul_f32_e32 v3, v232, v236
	v_cvt_pk_bf16_f32 v3, v3, s0
	ds_write_b16 v249, v3
	v_add_u32_e32 v249, v182, v249
	v_mul_f32_e32 v3, v233, v236
	v_cvt_pk_bf16_f32 v3, v3, s0
	ds_write_b16 v249, v3
	v_add_u32_e32 v249, v182, v249
	v_mul_f32_e32 v3, v234, v236
	v_cvt_pk_bf16_f32 v3, v3, s0
	ds_write_b16 v249, v3
	v_add_u32_e32 v249, v182, v249
	v_mul_f32_e32 v3, v235, v236
	v_cvt_pk_bf16_f32 v3, v3, s0
	ds_write_b16 v249, v3
	v_lshl_add_u32 v130, v184, 4, v130
	v_mov_b32_e32 v4, v130
	v_mul_f32_e32 v3, v160, v237
	v_cvt_pk_bf16_f32 v3, v3, s0
	ds_write_b16 v4, v3
	v_add_u32_e32 v4, v184, v4
	v_mul_f32_e32 v3, v161, v237
	v_cvt_pk_bf16_f32 v3, v3, s0
	ds_write_b16 v4, v3
	v_add_u32_e32 v4, v184, v4
	v_mul_f32_e32 v3, v162, v237
	v_cvt_pk_bf16_f32 v3, v3, s0
	ds_write_b16 v4, v3
	v_add_u32_e32 v4, v184, v4
	v_mul_f32_e32 v3, v163, v237
	v_cvt_pk_bf16_f32 v3, v3, s0
	ds_write_b16 v4, v3
	v_lshl_add_u32 v130, v184, 4, v130
	v_mov_b32_e32 v4, v130
	v_mul_f32_e32 v3, v122, v237
	v_cvt_pk_bf16_f32 v3, v3, s0
	ds_write_b16 v4, v3
	v_add_u32_e32 v4, v184, v4
	v_mul_f32_e32 v3, v123, v237
	v_cvt_pk_bf16_f32 v3, v3, s0
	ds_write_b16 v4, v3
	v_add_u32_e32 v4, v184, v4
	v_mul_f32_e32 v3, v124, v237
	v_cvt_pk_bf16_f32 v3, v3, s0
	ds_write_b16 v4, v3
	v_add_u32_e32 v4, v184, v4
	v_mul_f32_e32 v3, v125, v237
	v_cvt_pk_bf16_f32 v3, v3, s0
	ds_write_b16 v4, v3
	s_branch .Ls4o_end
.Ls4o2:
	s_waitcnt lgkmcnt(0)
	ds_write_b16 v249, v2
	v_add_u32_e32 v249, v182, v249
	ds_write_b16 v249, v2
	v_add_u32_e32 v249, v182, v249
	ds_write_b16 v249, v2
	v_add_u32_e32 v249, v182, v249
	ds_write_b16 v249, v2
	v_add_u32_e32 v249, v182, v249
	ds_write_b16 v249, v2
	v_add_u32_e32 v249, v182, v249
	ds_write_b16 v249, v2
	v_add_u32_e32 v249, v182, v249
	ds_write_b16 v249, v2
	v_add_u32_e32 v249, v182, v249
	ds_write_b16 v249, v2
	v_add_u32_e32 v249, v182, v249
	v_mul_f32_e32 v3, v232, v236
	v_cvt_pk_bf16_f32 v3, v3, s0
	ds_write_b16 v249, v3
	v_add_u32_e32 v249, v182, v249
	v_mul_f32_e32 v3, v233, v236
	v_cvt_pk_bf16_f32 v3, v3, s0
	ds_write_b16 v249, v3
	v_add_u32_e32 v249, v182, v249
	v_mul_f32_e32 v3, v234, v236
	v_cvt_pk_bf16_f32 v3, v3, s0
	ds_write_b16 v249, v3
	v_add_u32_e32 v249, v182, v249
	v_mul_f32_e32 v3, v235, v236
	v_cvt_pk_bf16_f32 v3, v3, s0
	ds_write_b16 v249, v3
	v_lshl_add_u32 v130, v184, 4, v130
	v_mov_b32_e32 v4, v130
	v_mul_f32_e32 v3, v160, v237
	v_cvt_pk_bf16_f32 v3, v3, s0
	ds_write_b16 v4, v3
	v_add_u32_e32 v4, v184, v4
	v_mul_f32_e32 v3, v161, v237
	v_cvt_pk_bf16_f32 v3, v3, s0
	ds_write_b16 v4, v3
	v_add_u32_e32 v4, v184, v4
	v_mul_f32_e32 v3, v162, v237
	v_cvt_pk_bf16_f32 v3, v3, s0
	ds_write_b16 v4, v3
	v_add_u32_e32 v4, v184, v4
	v_mul_f32_e32 v3, v163, v237
	v_cvt_pk_bf16_f32 v3, v3, s0
	ds_write_b16 v4, v3
	s_branch .Ls4o_end
.Ls4o3:
	s_waitcnt lgkmcnt(0)
	ds_write_b16 v249, v2
	v_add_u32_e32 v249, v182, v249
	ds_write_b16 v249, v2
	v_add_u32_e32 v249, v182, v249
	ds_write_b16 v249, v2
	v_add_u32_e32 v249, v182, v249
	ds_write_b16 v249, v2
	v_add_u32_e32 v249, v182, v249
	ds_write_b16 v249, v2
	v_add_u32_e32 v249, v182, v249
	ds_write_b16 v249, v2
	v_add_u32_e32 v249, v182, v249
	ds_write_b16 v249, v2
	v_add_u32_e32 v249, v182, v249
	ds_write_b16 v249, v2
	v_add_u32_e32 v249, v182, v249
	ds_write_b16 v249, v2
	v_add_u32_e32 v249, v182, v249
	ds_write_b16 v249, v2
	v_add_u32_e32 v249, v182, v249
	ds_write_b16 v249, v2
	v_add_u32_e32 v249, v182, v249
	ds_write_b16 v249, v2
	v_add_u32_e32 v249, v182, v249
	v_mul_f32_e32 v3, v232, v236
	v_cvt_pk_bf16_f32 v3, v3, s0
	ds_write_b16 v249, v3
	v_add_u32_e32 v249, v182, v249
	v_mul_f32_e32 v3, v233, v236
	v_cvt_pk_bf16_f32 v3, v3, s0
	ds_write_b16 v249, v3
	v_add_u32_e32 v249, v182, v249
	v_mul_f32_e32 v3, v234, v236
	v_cvt_pk_bf16_f32 v3, v3, s0
	ds_write_b16 v249, v3
	v_add_u32_e32 v249, v182, v249
	v_mul_f32_e32 v3, v235, v236
	v_cvt_pk_bf16_f32 v3, v3, s0
	ds_write_b16 v249, v3
